# P3/P6/P8 residual epilogues rewritten: 6-14 row-steps of loads in flight instead of 2, on top of LN hoist
# speedup vs baseline: 1.0021x; 1.0021x over previous
; __device__ __forceinline__ unsigned cvt_pk_bf16(float lo, float hi) { unsigned r; asm volatile("v_cvt_pk_bf16_f32 %0, %1, %2" : "=v"(r) : "v"(lo), "v"(hi)); return r; }
; #define PG8_GAS __attribute__((address_space(1)))
;     __device__ __forceinline__ void operator()(const f32x4 (&acc)[2][2][4][2], const Unit& u, int wr, int wc, int fr, int fq) const {
;         const int col0 = u.pn * BM + wc * 32 + 8 * fq; const int rowb = u.pm * BM + wr * 64 + fr;
;         const unsigned off0 = (unsigned)(rowb * 2048 + col0);
;     ...
; #pragma unroll
;         for (int bj = 0; bj < 2; ++bj) { const int c = bj * HALF;
;             f32x4 n0 = *(const PG8_GAS f32x4*)(res + PG8_ROFF(0) + c), n1 = *(const PG8_GAS f32x4*)(res + PG8_ROFF(0) + c + 4);
; #pragma unroll
;             for (int k = 0; k < 8; ++k) { const f32x4 r0 = n0, r1 = n1;
;                 if (k < 7) { n0 = *(const PG8_GAS f32x4*)(res + PG8_ROFF(k + 1) + c); n1 = *(const PG8_GAS f32x4*)(res + PG8_ROFF(k + 1) + c + 4); }
;                 const unsigned o = PG8_ROFF(k) + c;
;                 const f32x4 y0 = r0 * alpha + acc[k >> 2][bj][k & 3][0], y1 = r1 * alpha + acc[k >> 2][bj][k & 3][1];
;                 u32x4 w; w.x = cvt_pk_bf16(y0[0], y0[1]); w.y = cvt_pk_bf16(y0[2], y0[3]); w.z = cvt_pk_bf16(y1[0], y1[1]); w.w = cvt_pk_bf16(y1[2], y1[3]); *(PG8_GAS u32x4*)(out + o) = w; } }
.LBB0_396:
	s_lshl_b32 s21, s76, 8
	s_lshl_b32 s23, s28, 19
	s_add_i32 s23, s23, s21
	v_add_u32_e32 v136, s23, v155
	s_andn2_b64 vcc, exec, s[4:5]
	s_mov_b64 s[4:5], -1
	v_lshlrev_b32_e32 v212, 1, v136
	v_lshlrev_b32_e32 v136, 2, v136
	v_add_u32_e32 v150, 0x0, v136
	global_load_dwordx4 v[146:149], v150, s[10:11]
	global_load_dwordx4 v[150:153], v150, s[10:11] offset:16
	v_add_u32_e32 v164, 0x20000, v136
	global_load_dwordx4 v[160:163], v164, s[10:11]
	global_load_dwordx4 v[164:167], v164, s[10:11] offset:16
	v_add_u32_e32 v176, 0x40000, v136
	global_load_dwordx4 v[172:175], v176, s[10:11]
	global_load_dwordx4 v[176:179], v176, s[10:11] offset:16
	v_add_u32_e32 v184, 0x60000, v136
	global_load_dwordx4 v[180:183], v184, s[10:11]
	global_load_dwordx4 v[184:187], v184, s[10:11] offset:16
	v_add_u32_e32 v192, 0x100000, v136
	global_load_dwordx4 v[188:191], v192, s[10:11]
	global_load_dwordx4 v[192:195], v192, s[10:11] offset:16
	v_add_u32_e32 v200, 0x120000, v136
	global_load_dwordx4 v[196:199], v200, s[10:11]
	global_load_dwordx4 v[200:203], v200, s[10:11] offset:16
	v_add_u32_e32 v208, 0x140000, v136
	global_load_dwordx4 v[204:207], v208, s[10:11]
	global_load_dwordx4 v[208:211], v208, s[10:11] offset:16
	s_waitcnt vmcnt(12)
	v_pk_fma_f32 v[124:125], v[146:147], s[18:19], v[124:125] op_sel_hi:[1,0,1]
	v_pk_fma_f32 v[126:127], v[148:149], s[18:19], v[126:127] op_sel_hi:[1,0,1]
	v_pk_fma_f32 v[120:121], v[150:151], s[18:19], v[120:121] op_sel_hi:[1,0,1]
	v_pk_fma_f32 v[122:123], v[152:153], s[18:19], v[122:123] op_sel_hi:[1,0,1]
	v_cvt_pk_bf16_f32 v124, v124, v125
	v_cvt_pk_bf16_f32 v125, v126, v127
	v_cvt_pk_bf16_f32 v126, v120, v121
	v_cvt_pk_bf16_f32 v127, v122, v123
	v_add_u32_e32 v120, 0x0, v212
	global_store_dwordx4 v120, v[124:127], s[8:9]
	v_add_u32_e32 v150, 0x160000, v136
	global_load_dwordx4 v[146:149], v150, s[10:11]
	global_load_dwordx4 v[150:153], v150, s[10:11] offset:16
	s_waitcnt vmcnt(13)
	v_pk_fma_f32 v[116:117], v[160:161], s[18:19], v[116:117] op_sel_hi:[1,0,1]
	v_pk_fma_f32 v[118:119], v[162:163], s[18:19], v[118:119] op_sel_hi:[1,0,1]
	v_pk_fma_f32 v[112:113], v[164:165], s[18:19], v[112:113] op_sel_hi:[1,0,1]
	v_pk_fma_f32 v[114:115], v[166:167], s[18:19], v[114:115] op_sel_hi:[1,0,1]
	v_cvt_pk_bf16_f32 v116, v116, v117
	v_cvt_pk_bf16_f32 v117, v118, v119
	v_cvt_pk_bf16_f32 v118, v112, v113
	v_cvt_pk_bf16_f32 v119, v114, v115
	v_add_u32_e32 v112, 0x10000, v212
	global_store_dwordx4 v112, v[116:119], s[8:9]
	v_add_u32_e32 v164, 0x0, v136
	global_load_dwordx4 v[160:163], v164, s[10:11] offset:512
	global_load_dwordx4 v[164:167], v164, s[10:11] offset:528
	s_waitcnt vmcnt(14)
	v_pk_fma_f32 v[108:109], v[172:173], s[18:19], v[108:109] op_sel_hi:[1,0,1]
	v_pk_fma_f32 v[110:111], v[174:175], s[18:19], v[110:111] op_sel_hi:[1,0,1]
	v_pk_fma_f32 v[104:105], v[176:177], s[18:19], v[104:105] op_sel_hi:[1,0,1]
	v_pk_fma_f32 v[106:107], v[178:179], s[18:19], v[106:107] op_sel_hi:[1,0,1]
	v_cvt_pk_bf16_f32 v108, v108, v109
	v_cvt_pk_bf16_f32 v109, v110, v111
	v_cvt_pk_bf16_f32 v110, v104, v105
	v_cvt_pk_bf16_f32 v111, v106, v107
	v_add_u32_e32 v104, 0x20000, v212
	global_store_dwordx4 v104, v[108:111], s[8:9]
	v_add_u32_e32 v176, 0x20000, v136
	global_load_dwordx4 v[172:175], v176, s[10:11] offset:512
	global_load_dwordx4 v[176:179], v176, s[10:11] offset:528
	s_waitcnt vmcnt(15)
	v_pk_fma_f32 v[100:101], v[180:181], s[18:19], v[100:101] op_sel_hi:[1,0,1]
	v_pk_fma_f32 v[102:103], v[182:183], s[18:19], v[102:103] op_sel_hi:[1,0,1]
	v_pk_fma_f32 v[96:97], v[184:185], s[18:19], v[96:97] op_sel_hi:[1,0,1]
	v_pk_fma_f32 v[98:99], v[186:187], s[18:19], v[98:99] op_sel_hi:[1,0,1]
	v_cvt_pk_bf16_f32 v100, v100, v101
	v_cvt_pk_bf16_f32 v101, v102, v103
	v_cvt_pk_bf16_f32 v102, v96, v97
	v_cvt_pk_bf16_f32 v103, v98, v99
	v_add_u32_e32 v96, 0x30000, v212
	global_store_dwordx4 v96, v[100:103], s[8:9]
	v_add_u32_e32 v184, 0x40000, v136
	global_load_dwordx4 v[180:183], v184, s[10:11] offset:512
	global_load_dwordx4 v[184:187], v184, s[10:11] offset:528
	s_waitcnt vmcnt(16)
	v_pk_fma_f32 v[92:93], v[188:189], s[18:19], v[92:93] op_sel_hi:[1,0,1]
	v_pk_fma_f32 v[94:95], v[190:191], s[18:19], v[94:95] op_sel_hi:[1,0,1]
	v_pk_fma_f32 v[88:89], v[192:193], s[18:19], v[88:89] op_sel_hi:[1,0,1]
	v_pk_fma_f32 v[90:91], v[194:195], s[18:19], v[90:91] op_sel_hi:[1,0,1]
	v_cvt_pk_bf16_f32 v92, v92, v93
	v_cvt_pk_bf16_f32 v93, v94, v95
	v_cvt_pk_bf16_f32 v94, v88, v89
	v_cvt_pk_bf16_f32 v95, v90, v91
	v_add_u32_e32 v88, 0x80000, v212
	global_store_dwordx4 v88, v[92:95], s[8:9]
	v_add_u32_e32 v192, 0x60000, v136
	global_load_dwordx4 v[188:191], v192, s[10:11] offset:512
	global_load_dwordx4 v[192:195], v192, s[10:11] offset:528
	s_waitcnt vmcnt(17)
	v_pk_fma_f32 v[84:85], v[196:197], s[18:19], v[84:85] op_sel_hi:[1,0,1]
	v_pk_fma_f32 v[86:87], v[198:199], s[18:19], v[86:87] op_sel_hi:[1,0,1]
	v_pk_fma_f32 v[80:81], v[200:201], s[18:19], v[80:81] op_sel_hi:[1,0,1]
	v_pk_fma_f32 v[82:83], v[202:203], s[18:19], v[82:83] op_sel_hi:[1,0,1]
	v_cvt_pk_bf16_f32 v84, v84, v85
	v_cvt_pk_bf16_f32 v85, v86, v87
	v_cvt_pk_bf16_f32 v86, v80, v81
	v_cvt_pk_bf16_f32 v87, v82, v83
	v_add_u32_e32 v80, 0x90000, v212
	global_store_dwordx4 v80, v[84:87], s[8:9]
	v_add_u32_e32 v200, 0x100000, v136
	global_load_dwordx4 v[196:199], v200, s[10:11] offset:512
	global_load_dwordx4 v[200:203], v200, s[10:11] offset:528
	s_waitcnt vmcnt(18)
; __device__ __forceinline__ unsigned cvt_pk_bf16(float lo, float hi) { unsigned r; asm volatile("v_cvt_pk_bf16_f32 %0, %1, %2" : "=v"(r) : "v"(lo), "v"(hi)); return r; }
; #define PG8_GAS __attribute__((address_space(1)))
;     __device__ __forceinline__ void operator()(const f32x4 (&acc)[2][2][4][2], const Unit& u, int wr, int wc, int fr, int fq) const {
;     ...
;             for (int k = 0; k < 8; ++k) { const f32x4 r0 = n0, r1 = n1;
;                 if (k < 7) { n0 = *(const PG8_GAS f32x4*)(res + PG8_ROFF(k + 1) + c); n1 = *(const PG8_GAS f32x4*)(res + PG8_ROFF(k + 1) + c + 4); }
;                 const unsigned o = PG8_ROFF(k) + c;
;                 const f32x4 y0 = r0 * alpha + acc[k >> 2][bj][k & 3][0], y1 = r1 * alpha + acc[k >> 2][bj][k & 3][1];
;                 u32x4 w; w.x = cvt_pk_bf16(y0[0], y0[1]); w.y = cvt_pk_bf16(y0[2], y0[3]); w.z = cvt_pk_bf16(y1[0], y1[1]); w.w = cvt_pk_bf16(y1[2], y1[3]); *(PG8_GAS u32x4*)(out + o) = w; } }
	v_pk_fma_f32 v[76:77], v[204:205], s[18:19], v[76:77] op_sel_hi:[1,0,1]
	v_pk_fma_f32 v[78:79], v[206:207], s[18:19], v[78:79] op_sel_hi:[1,0,1]
	v_pk_fma_f32 v[72:73], v[208:209], s[18:19], v[72:73] op_sel_hi:[1,0,1]
	v_pk_fma_f32 v[74:75], v[210:211], s[18:19], v[74:75] op_sel_hi:[1,0,1]
	v_cvt_pk_bf16_f32 v76, v76, v77
	v_cvt_pk_bf16_f32 v77, v78, v79
	v_cvt_pk_bf16_f32 v78, v72, v73
	v_cvt_pk_bf16_f32 v79, v74, v75
	v_add_u32_e32 v72, 0xa0000, v212
	global_store_dwordx4 v72, v[76:79], s[8:9]
	v_add_u32_e32 v208, 0x120000, v136
	global_load_dwordx4 v[204:207], v208, s[10:11] offset:512
	global_load_dwordx4 v[208:211], v208, s[10:11] offset:528
	s_waitcnt vmcnt(18)
	v_pk_fma_f32 v[68:69], v[146:147], s[18:19], v[68:69] op_sel_hi:[1,0,1]
	v_pk_fma_f32 v[70:71], v[148:149], s[18:19], v[70:71] op_sel_hi:[1,0,1]
	v_pk_fma_f32 v[64:65], v[150:151], s[18:19], v[64:65] op_sel_hi:[1,0,1]
	v_pk_fma_f32 v[66:67], v[152:153], s[18:19], v[66:67] op_sel_hi:[1,0,1]
	v_cvt_pk_bf16_f32 v68, v68, v69
	v_cvt_pk_bf16_f32 v69, v70, v71
	v_cvt_pk_bf16_f32 v70, v64, v65
	v_cvt_pk_bf16_f32 v71, v66, v67
	v_add_u32_e32 v64, 0xb0000, v212
	global_store_dwordx4 v64, v[68:71], s[8:9]
	v_add_u32_e32 v150, 0x140000, v136
	global_load_dwordx4 v[146:149], v150, s[10:11] offset:512
	global_load_dwordx4 v[150:153], v150, s[10:11] offset:528
	s_waitcnt vmcnt(18)
	v_pk_fma_f32 v[60:61], v[160:161], s[18:19], v[60:61] op_sel_hi:[1,0,1]
	v_pk_fma_f32 v[62:63], v[162:163], s[18:19], v[62:63] op_sel_hi:[1,0,1]
	v_pk_fma_f32 v[56:57], v[164:165], s[18:19], v[56:57] op_sel_hi:[1,0,1]
	v_pk_fma_f32 v[58:59], v[166:167], s[18:19], v[58:59] op_sel_hi:[1,0,1]
	v_cvt_pk_bf16_f32 v60, v60, v61
	v_cvt_pk_bf16_f32 v61, v62, v63
	v_cvt_pk_bf16_f32 v62, v56, v57
	v_cvt_pk_bf16_f32 v63, v58, v59
	v_add_u32_e32 v56, 0x0, v212
	global_store_dwordx4 v56, v[60:63], s[8:9] offset:256
	v_add_u32_e32 v164, 0x160000, v136
	global_load_dwordx4 v[160:163], v164, s[10:11] offset:512
	global_load_dwordx4 v[164:167], v164, s[10:11] offset:528
	s_waitcnt vmcnt(18)
	v_pk_fma_f32 v[52:53], v[172:173], s[18:19], v[52:53] op_sel_hi:[1,0,1]
	v_pk_fma_f32 v[54:55], v[174:175], s[18:19], v[54:55] op_sel_hi:[1,0,1]
	v_pk_fma_f32 v[48:49], v[176:177], s[18:19], v[48:49] op_sel_hi:[1,0,1]
	v_pk_fma_f32 v[50:51], v[178:179], s[18:19], v[50:51] op_sel_hi:[1,0,1]
	v_cvt_pk_bf16_f32 v52, v52, v53
	v_cvt_pk_bf16_f32 v53, v54, v55
	v_cvt_pk_bf16_f32 v54, v48, v49
	v_cvt_pk_bf16_f32 v55, v50, v51
	v_add_u32_e32 v48, 0x10000, v212
	global_store_dwordx4 v48, v[52:55], s[8:9] offset:256
	s_waitcnt vmcnt(16)
	v_pk_fma_f32 v[44:45], v[180:181], s[18:19], v[44:45] op_sel_hi:[1,0,1]
	v_pk_fma_f32 v[46:47], v[182:183], s[18:19], v[46:47] op_sel_hi:[1,0,1]
	v_pk_fma_f32 v[40:41], v[184:185], s[18:19], v[40:41] op_sel_hi:[1,0,1]
	v_pk_fma_f32 v[42:43], v[186:187], s[18:19], v[42:43] op_sel_hi:[1,0,1]
	v_cvt_pk_bf16_f32 v44, v44, v45
	v_cvt_pk_bf16_f32 v45, v46, v47
	v_cvt_pk_bf16_f32 v46, v40, v41
	v_cvt_pk_bf16_f32 v47, v42, v43
	v_add_u32_e32 v40, 0x20000, v212
	global_store_dwordx4 v40, v[44:47], s[8:9] offset:256
	s_waitcnt vmcnt(14)
	v_pk_fma_f32 v[36:37], v[188:189], s[18:19], v[36:37] op_sel_hi:[1,0,1]
	v_pk_fma_f32 v[38:39], v[190:191], s[18:19], v[38:39] op_sel_hi:[1,0,1]
	v_pk_fma_f32 v[32:33], v[192:193], s[18:19], v[32:33] op_sel_hi:[1,0,1]
	v_pk_fma_f32 v[34:35], v[194:195], s[18:19], v[34:35] op_sel_hi:[1,0,1]
	v_cvt_pk_bf16_f32 v36, v36, v37
	v_cvt_pk_bf16_f32 v37, v38, v39
	v_cvt_pk_bf16_f32 v38, v32, v33
	v_cvt_pk_bf16_f32 v39, v34, v35
	v_add_u32_e32 v32, 0x30000, v212
	global_store_dwordx4 v32, v[36:39], s[8:9] offset:256
	s_waitcnt vmcnt(12)
	v_pk_fma_f32 v[28:29], v[196:197], s[18:19], v[28:29] op_sel_hi:[1,0,1]
	v_pk_fma_f32 v[30:31], v[198:199], s[18:19], v[30:31] op_sel_hi:[1,0,1]
	v_pk_fma_f32 v[24:25], v[200:201], s[18:19], v[24:25] op_sel_hi:[1,0,1]
	v_pk_fma_f32 v[26:27], v[202:203], s[18:19], v[26:27] op_sel_hi:[1,0,1]
	v_cvt_pk_bf16_f32 v28, v28, v29
	v_cvt_pk_bf16_f32 v29, v30, v31
	v_cvt_pk_bf16_f32 v30, v24, v25
	v_cvt_pk_bf16_f32 v31, v26, v27
	v_add_u32_e32 v24, 0x80000, v212
	global_store_dwordx4 v24, v[28:31], s[8:9] offset:256
	s_waitcnt vmcnt(10)
	v_pk_fma_f32 v[20:21], v[204:205], s[18:19], v[20:21] op_sel_hi:[1,0,1]
	v_pk_fma_f32 v[22:23], v[206:207], s[18:19], v[22:23] op_sel_hi:[1,0,1]
	v_pk_fma_f32 v[16:17], v[208:209], s[18:19], v[16:17] op_sel_hi:[1,0,1]
	v_pk_fma_f32 v[18:19], v[210:211], s[18:19], v[18:19] op_sel_hi:[1,0,1]
	v_cvt_pk_bf16_f32 v20, v20, v21
	v_cvt_pk_bf16_f32 v21, v22, v23
	v_cvt_pk_bf16_f32 v22, v16, v17
	v_cvt_pk_bf16_f32 v23, v18, v19
	v_add_u32_e32 v16, 0x90000, v212
	global_store_dwordx4 v16, v[20:23], s[8:9] offset:256
	s_waitcnt vmcnt(8)
	v_pk_fma_f32 v[12:13], v[146:147], s[18:19], v[12:13] op_sel_hi:[1,0,1]
	v_pk_fma_f32 v[14:15], v[148:149], s[18:19], v[14:15] op_sel_hi:[1,0,1]
	v_pk_fma_f32 v[8:9], v[150:151], s[18:19], v[8:9] op_sel_hi:[1,0,1]
	v_pk_fma_f32 v[10:11], v[152:153], s[18:19], v[10:11] op_sel_hi:[1,0,1]
	v_cvt_pk_bf16_f32 v12, v12, v13
	v_cvt_pk_bf16_f32 v13, v14, v15
	v_cvt_pk_bf16_f32 v14, v8, v9
	v_cvt_pk_bf16_f32 v15, v10, v11
	v_add_u32_e32 v8, 0xa0000, v212
	global_store_dwordx4 v8, v[12:15], s[8:9] offset:256
	s_waitcnt vmcnt(6)
	v_pk_fma_f32 v[4:5], v[160:161], s[18:19], v[4:5] op_sel_hi:[1,0,1]
	v_pk_fma_f32 v[6:7], v[162:163], s[18:19], v[6:7] op_sel_hi:[1,0,1]
	v_pk_fma_f32 v[0:1], v[164:165], s[18:19], v[0:1] op_sel_hi:[1,0,1]
	v_pk_fma_f32 v[2:3], v[166:167], s[18:19], v[2:3] op_sel_hi:[1,0,1]
	v_cvt_pk_bf16_f32 v4, v4, v5
	v_cvt_pk_bf16_f32 v5, v6, v7
	v_cvt_pk_bf16_f32 v6, v0, v1
	v_cvt_pk_bf16_f32 v7, v2, v3
	v_add_u32_e32 v0, 0xb0000, v212
	global_store_dwordx4 v0, v[4:7], s[8:9] offset:256
	s_cbranch_vccnz .LBB0_385
	s_andn2_b64 vcc, exec, s[12:13]
	s_cbranch_vccnz .LBB0_384
	s_barrier
	s_branch .LBB0_384

; __device__ __forceinline__ unsigned cvt_pk_bf16(float lo, float hi) { unsigned r; asm volatile("v_cvt_pk_bf16_f32 %0, %1, %2" : "=v"(r) : "v"(lo), "v"(hi)); return r; }
; __device__ __forceinline__ float bf_lo(unsigned w) { return __uint_as_float(w << 16); }
; __device__ __forceinline__ float bf_hi(unsigned w) { return __uint_as_float(w & 0xffff0000u); }
; #define PG8_GAS __attribute__((address_space(1)))
;     __device__ __forceinline__ void operator()(const f32x4 (&acc)[2][2][4][2], const Unit& u, int wr, int wc, int fr, int fq) const {
;         const int col0 = u.pn * BM + wc * 32 + 8 * fq; const int rowb = u.pm * BM + wr * 64 + fr;
;         const unsigned off0 = (unsigned)(rowb * 2048 + col0);
;     ...
; #pragma unroll
;         for (int bj = 0; bj < 2; ++bj) { const int c = bj * HALF;
;             u32x4 nn = *(const PG8_GAS u32x4*)(res + PG8_ROFF(0) + c);
; #pragma unroll
;             for (int k = 0; k < 8; ++k) { const u32x4 rw = nn;
;                 if (k < 7) nn = *(const PG8_GAS u32x4*)(res + PG8_ROFF(k + 1) + c);
;                 const f32x4 r0 = (f32x4){bf_lo(rw.x), bf_hi(rw.x), bf_lo(rw.y), bf_hi(rw.y)}, r1 = (f32x4){bf_lo(rw.z), bf_hi(rw.z), bf_lo(rw.w), bf_hi(rw.w)};
;                 const unsigned o = PG8_ROFF(k) + c;
;                 const f32x4 y0 = r0 * alpha + acc[k >> 2][bj][k & 3][0], y1 = r1 * alpha + acc[k >> 2][bj][k & 3][1];
;                 u32x4 w; w.x = cvt_pk_bf16(y0[0], y0[1]); w.y = cvt_pk_bf16(y0[2], y0[3]); w.z = cvt_pk_bf16(y1[0], y1[1]); w.w = cvt_pk_bf16(y1[2], y1[3]); *(PG8_GAS u32x4*)(out + o) = w; } }
.LBB0_609:
	s_lshl_b32 s24, s66, 8
	s_lshl_b32 s25, s57, 19
	s_add_i32 s25, s25, s24
	v_add_u32_e32 v140, s25, v139
	s_and_b64 vcc, exec, s[4:5]
	s_mov_b64 s[4:5], -1
	v_lshlrev_b32_e32 v140, 1, v140
	v_add_u32_e32 v150, 0x0, v140
	global_load_dwordx4 v[150:153], v150, s[68:69]
	v_add_u32_e32 v154, 0x10000, v140
	global_load_dwordx4 v[154:157], v154, s[68:69]
	v_add_u32_e32 v162, 0x20000, v140
	global_load_dwordx4 v[162:165], v162, s[68:69]
	v_add_u32_e32 v166, 0x30000, v140
	global_load_dwordx4 v[166:169], v166, s[68:69]
	v_add_u32_e32 v174, 0x80000, v140
	global_load_dwordx4 v[174:177], v174, s[68:69]
	v_add_u32_e32 v178, 0x90000, v140
	global_load_dwordx4 v[178:181], v178, s[68:69]
	v_add_u32_e32 v182, 0xa0000, v140
	global_load_dwordx4 v[182:185], v182, s[68:69]
	v_add_u32_e32 v186, 0xb0000, v140
	global_load_dwordx4 v[186:189], v186, s[68:69]
	v_add_u32_e32 v190, 0x0, v140
	global_load_dwordx4 v[190:193], v190, s[68:69] offset:256
	v_add_u32_e32 v194, 0x10000, v140
	global_load_dwordx4 v[194:197], v194, s[68:69] offset:256
	v_add_u32_e32 v198, 0x20000, v140
	global_load_dwordx4 v[198:201], v198, s[68:69] offset:256
	v_add_u32_e32 v202, 0x30000, v140
	global_load_dwordx4 v[202:205], v202, s[68:69] offset:256
	v_add_u32_e32 v206, 0x80000, v140
	global_load_dwordx4 v[206:209], v206, s[68:69] offset:256
	v_add_u32_e32 v210, 0x90000, v140
	global_load_dwordx4 v[210:213], v210, s[68:69] offset:256
	s_waitcnt vmcnt(13)
	v_lshlrev_b32_e32 v214, 16, v151
	v_and_b32_e32 v215, 0xffff0000, v151
	v_and_b32_e32 v151, 0xffff0000, v150
	v_lshlrev_b32_e32 v150, 16, v150
	v_pk_fma_f32 v[124:125], v[150:151], s[20:21], v[124:125] op_sel_hi:[1,0,1]
	v_pk_fma_f32 v[126:127], v[214:215], s[20:21], v[126:127] op_sel_hi:[1,0,1]
	v_lshlrev_b32_e32 v214, 16, v153
	v_and_b32_e32 v215, 0xffff0000, v153
	v_and_b32_e32 v153, 0xffff0000, v152
	v_lshlrev_b32_e32 v152, 16, v152
	v_pk_fma_f32 v[120:121], v[152:153], s[20:21], v[120:121] op_sel_hi:[1,0,1]
	v_pk_fma_f32 v[122:123], v[214:215], s[20:21], v[122:123] op_sel_hi:[1,0,1]
	v_cvt_pk_bf16_f32 v124, v124, v125
	v_cvt_pk_bf16_f32 v125, v126, v127
	v_cvt_pk_bf16_f32 v126, v120, v121
	v_cvt_pk_bf16_f32 v127, v122, v123
	v_add_u32_e32 v120, 0x0, v140
	global_store_dwordx4 v120, v[124:127], s[8:9]
	v_add_u32_e32 v150, 0xa0000, v140
	global_load_dwordx4 v[150:153], v150, s[68:69] offset:256
	s_waitcnt vmcnt(14)
	v_lshlrev_b32_e32 v214, 16, v155
	v_and_b32_e32 v215, 0xffff0000, v155
	v_and_b32_e32 v155, 0xffff0000, v154
	v_lshlrev_b32_e32 v154, 16, v154
	v_pk_fma_f32 v[116:117], v[154:155], s[20:21], v[116:117] op_sel_hi:[1,0,1]
	v_pk_fma_f32 v[118:119], v[214:215], s[20:21], v[118:119] op_sel_hi:[1,0,1]
	v_lshlrev_b32_e32 v214, 16, v157
	v_and_b32_e32 v215, 0xffff0000, v157
	v_and_b32_e32 v157, 0xffff0000, v156
	v_lshlrev_b32_e32 v156, 16, v156
	v_pk_fma_f32 v[112:113], v[156:157], s[20:21], v[112:113] op_sel_hi:[1,0,1]
	v_pk_fma_f32 v[114:115], v[214:215], s[20:21], v[114:115] op_sel_hi:[1,0,1]
	v_cvt_pk_bf16_f32 v116, v116, v117
	v_cvt_pk_bf16_f32 v117, v118, v119
	v_cvt_pk_bf16_f32 v118, v112, v113
	v_cvt_pk_bf16_f32 v119, v114, v115
	v_add_u32_e32 v112, 0x10000, v140
	global_store_dwordx4 v112, v[116:119], s[8:9]
	v_add_u32_e32 v154, 0xb0000, v140
	global_load_dwordx4 v[154:157], v154, s[68:69] offset:256
	s_waitcnt vmcnt(15)
	v_lshlrev_b32_e32 v214, 16, v163
	v_and_b32_e32 v215, 0xffff0000, v163
	v_and_b32_e32 v163, 0xffff0000, v162
	v_lshlrev_b32_e32 v162, 16, v162
	v_pk_fma_f32 v[108:109], v[162:163], s[20:21], v[108:109] op_sel_hi:[1,0,1]
	v_pk_fma_f32 v[110:111], v[214:215], s[20:21], v[110:111] op_sel_hi:[1,0,1]
	v_lshlrev_b32_e32 v214, 16, v165
	v_and_b32_e32 v215, 0xffff0000, v165
	v_and_b32_e32 v165, 0xffff0000, v164
	v_lshlrev_b32_e32 v164, 16, v164
	v_pk_fma_f32 v[104:105], v[164:165], s[20:21], v[104:105] op_sel_hi:[1,0,1]
	v_pk_fma_f32 v[106:107], v[214:215], s[20:21], v[106:107] op_sel_hi:[1,0,1]
	v_cvt_pk_bf16_f32 v108, v108, v109
	v_cvt_pk_bf16_f32 v109, v110, v111
	v_cvt_pk_bf16_f32 v110, v104, v105
	v_cvt_pk_bf16_f32 v111, v106, v107
	v_add_u32_e32 v104, 0x20000, v140
	global_store_dwordx4 v104, v[108:111], s[8:9]
	s_waitcnt vmcnt(15)
	v_lshlrev_b32_e32 v214, 16, v167
	v_and_b32_e32 v215, 0xffff0000, v167
	v_and_b32_e32 v167, 0xffff0000, v166
	v_lshlrev_b32_e32 v166, 16, v166
	v_pk_fma_f32 v[100:101], v[166:167], s[20:21], v[100:101] op_sel_hi:[1,0,1]
	v_pk_fma_f32 v[102:103], v[214:215], s[20:21], v[102:103] op_sel_hi:[1,0,1]
	v_lshlrev_b32_e32 v214, 16, v169
	v_and_b32_e32 v215, 0xffff0000, v169
	v_and_b32_e32 v169, 0xffff0000, v168
	v_lshlrev_b32_e32 v168, 16, v168
	v_pk_fma_f32 v[96:97], v[168:169], s[20:21], v[96:97] op_sel_hi:[1,0,1]
	v_pk_fma_f32 v[98:99], v[214:215], s[20:21], v[98:99] op_sel_hi:[1,0,1]
	v_cvt_pk_bf16_f32 v100, v100, v101
	v_cvt_pk_bf16_f32 v101, v102, v103
	v_cvt_pk_bf16_f32 v102, v96, v97
	v_cvt_pk_bf16_f32 v103, v98, v99
	v_add_u32_e32 v96, 0x30000, v140
	global_store_dwordx4 v96, v[100:103], s[8:9]
	s_waitcnt vmcnt(15)
	v_lshlrev_b32_e32 v214, 16, v175
	v_and_b32_e32 v215, 0xffff0000, v175
	v_and_b32_e32 v175, 0xffff0000, v174
	v_lshlrev_b32_e32 v174, 16, v174
	v_pk_fma_f32 v[92:93], v[174:175], s[20:21], v[92:93] op_sel_hi:[1,0,1]
	v_pk_fma_f32 v[94:95], v[214:215], s[20:21], v[94:95] op_sel_hi:[1,0,1]
	v_lshlrev_b32_e32 v214, 16, v177
	v_and_b32_e32 v215, 0xffff0000, v177
	v_and_b32_e32 v177, 0xffff0000, v176
	v_lshlrev_b32_e32 v176, 16, v176
	v_pk_fma_f32 v[88:89], v[176:177], s[20:21], v[88:89] op_sel_hi:[1,0,1]
	v_pk_fma_f32 v[90:91], v[214:215], s[20:21], v[90:91] op_sel_hi:[1,0,1]
	v_cvt_pk_bf16_f32 v92, v92, v93
	v_cvt_pk_bf16_f32 v93, v94, v95
	v_cvt_pk_bf16_f32 v94, v88, v89
	v_cvt_pk_bf16_f32 v95, v90, v91
	v_add_u32_e32 v88, 0x80000, v140
	global_store_dwordx4 v88, v[92:95], s[8:9]
	s_waitcnt vmcnt(15)
; __device__ __forceinline__ unsigned cvt_pk_bf16(float lo, float hi) { unsigned r; asm volatile("v_cvt_pk_bf16_f32 %0, %1, %2" : "=v"(r) : "v"(lo), "v"(hi)); return r; }
; __device__ __forceinline__ float bf_lo(unsigned w) { return __uint_as_float(w << 16); }
; __device__ __forceinline__ float bf_hi(unsigned w) { return __uint_as_float(w & 0xffff0000u); }
; #define PG8_GAS __attribute__((address_space(1)))
;     __device__ __forceinline__ void operator()(const f32x4 (&acc)[2][2][4][2], const Unit& u, int wr, int wc, int fr, int fq) const {
;         const int col0 = u.pn * BM + wc * 32 + 8 * fq; const int rowb = u.pm * BM + wr * 64 + fr;
;         const unsigned off0 = (unsigned)(rowb * 2048 + col0);
;     ...
; #pragma unroll
;         for (int bj = 0; bj < 2; ++bj) { const int c = bj * HALF;
;             u32x4 nn = *(const PG8_GAS u32x4*)(res + PG8_ROFF(0) + c);
; #pragma unroll
;             for (int k = 0; k < 8; ++k) { const u32x4 rw = nn;
;                 if (k < 7) nn = *(const PG8_GAS u32x4*)(res + PG8_ROFF(k + 1) + c);
;                 const f32x4 r0 = (f32x4){bf_lo(rw.x), bf_hi(rw.x), bf_lo(rw.y), bf_hi(rw.y)}, r1 = (f32x4){bf_lo(rw.z), bf_hi(rw.z), bf_lo(rw.w), bf_hi(rw.w)};
;                 const unsigned o = PG8_ROFF(k) + c;
;                 const f32x4 y0 = r0 * alpha + acc[k >> 2][bj][k & 3][0], y1 = r1 * alpha + acc[k >> 2][bj][k & 3][1];
;                 u32x4 w; w.x = cvt_pk_bf16(y0[0], y0[1]); w.y = cvt_pk_bf16(y0[2], y0[3]); w.z = cvt_pk_bf16(y1[0], y1[1]); w.w = cvt_pk_bf16(y1[2], y1[3]); *(PG8_GAS u32x4*)(out + o) = w; } }
	v_lshlrev_b32_e32 v214, 16, v179
	v_and_b32_e32 v215, 0xffff0000, v179
	v_and_b32_e32 v179, 0xffff0000, v178
	v_lshlrev_b32_e32 v178, 16, v178
	v_pk_fma_f32 v[84:85], v[178:179], s[20:21], v[84:85] op_sel_hi:[1,0,1]
	v_pk_fma_f32 v[86:87], v[214:215], s[20:21], v[86:87] op_sel_hi:[1,0,1]
	v_lshlrev_b32_e32 v214, 16, v181
	v_and_b32_e32 v215, 0xffff0000, v181
	v_and_b32_e32 v181, 0xffff0000, v180
	v_lshlrev_b32_e32 v180, 16, v180
	v_pk_fma_f32 v[80:81], v[180:181], s[20:21], v[80:81] op_sel_hi:[1,0,1]
	v_pk_fma_f32 v[82:83], v[214:215], s[20:21], v[82:83] op_sel_hi:[1,0,1]
	v_cvt_pk_bf16_f32 v84, v84, v85
	v_cvt_pk_bf16_f32 v85, v86, v87
	v_cvt_pk_bf16_f32 v86, v80, v81
	v_cvt_pk_bf16_f32 v87, v82, v83
	v_add_u32_e32 v80, 0x90000, v140
	global_store_dwordx4 v80, v[84:87], s[8:9]
	s_waitcnt vmcnt(15)
	v_lshlrev_b32_e32 v214, 16, v183
	v_and_b32_e32 v215, 0xffff0000, v183
	v_and_b32_e32 v183, 0xffff0000, v182
	v_lshlrev_b32_e32 v182, 16, v182
	v_pk_fma_f32 v[76:77], v[182:183], s[20:21], v[76:77] op_sel_hi:[1,0,1]
	v_pk_fma_f32 v[78:79], v[214:215], s[20:21], v[78:79] op_sel_hi:[1,0,1]
	v_lshlrev_b32_e32 v214, 16, v185
	v_and_b32_e32 v215, 0xffff0000, v185
	v_and_b32_e32 v185, 0xffff0000, v184
	v_lshlrev_b32_e32 v184, 16, v184
	v_pk_fma_f32 v[72:73], v[184:185], s[20:21], v[72:73] op_sel_hi:[1,0,1]
	v_pk_fma_f32 v[74:75], v[214:215], s[20:21], v[74:75] op_sel_hi:[1,0,1]
	v_cvt_pk_bf16_f32 v76, v76, v77
	v_cvt_pk_bf16_f32 v77, v78, v79
	v_cvt_pk_bf16_f32 v78, v72, v73
	v_cvt_pk_bf16_f32 v79, v74, v75
	v_add_u32_e32 v72, 0xa0000, v140
	global_store_dwordx4 v72, v[76:79], s[8:9]
	s_waitcnt vmcnt(15)
	v_lshlrev_b32_e32 v214, 16, v187
	v_and_b32_e32 v215, 0xffff0000, v187
	v_and_b32_e32 v187, 0xffff0000, v186
	v_lshlrev_b32_e32 v186, 16, v186
	v_pk_fma_f32 v[68:69], v[186:187], s[20:21], v[68:69] op_sel_hi:[1,0,1]
	v_pk_fma_f32 v[70:71], v[214:215], s[20:21], v[70:71] op_sel_hi:[1,0,1]
	v_lshlrev_b32_e32 v214, 16, v189
	v_and_b32_e32 v215, 0xffff0000, v189
	v_and_b32_e32 v189, 0xffff0000, v188
	v_lshlrev_b32_e32 v188, 16, v188
	v_pk_fma_f32 v[64:65], v[188:189], s[20:21], v[64:65] op_sel_hi:[1,0,1]
	v_pk_fma_f32 v[66:67], v[214:215], s[20:21], v[66:67] op_sel_hi:[1,0,1]
	v_cvt_pk_bf16_f32 v68, v68, v69
	v_cvt_pk_bf16_f32 v69, v70, v71
	v_cvt_pk_bf16_f32 v70, v64, v65
	v_cvt_pk_bf16_f32 v71, v66, v67
	v_add_u32_e32 v64, 0xb0000, v140
	global_store_dwordx4 v64, v[68:71], s[8:9]
	s_waitcnt vmcnt(15)
	v_lshlrev_b32_e32 v214, 16, v191
	v_and_b32_e32 v215, 0xffff0000, v191
	v_and_b32_e32 v191, 0xffff0000, v190
	v_lshlrev_b32_e32 v190, 16, v190
	v_pk_fma_f32 v[60:61], v[190:191], s[20:21], v[60:61] op_sel_hi:[1,0,1]
	v_pk_fma_f32 v[62:63], v[214:215], s[20:21], v[62:63] op_sel_hi:[1,0,1]
	v_lshlrev_b32_e32 v214, 16, v193
	v_and_b32_e32 v215, 0xffff0000, v193
	v_and_b32_e32 v193, 0xffff0000, v192
	v_lshlrev_b32_e32 v192, 16, v192
	v_pk_fma_f32 v[56:57], v[192:193], s[20:21], v[56:57] op_sel_hi:[1,0,1]
	v_pk_fma_f32 v[58:59], v[214:215], s[20:21], v[58:59] op_sel_hi:[1,0,1]
	v_cvt_pk_bf16_f32 v60, v60, v61
	v_cvt_pk_bf16_f32 v61, v62, v63
	v_cvt_pk_bf16_f32 v62, v56, v57
	v_cvt_pk_bf16_f32 v63, v58, v59
	v_add_u32_e32 v56, 0x0, v140
	global_store_dwordx4 v56, v[60:63], s[8:9] offset:256
	s_waitcnt vmcnt(15)
	v_lshlrev_b32_e32 v214, 16, v195
	v_and_b32_e32 v215, 0xffff0000, v195
	v_and_b32_e32 v195, 0xffff0000, v194
	v_lshlrev_b32_e32 v194, 16, v194
	v_pk_fma_f32 v[52:53], v[194:195], s[20:21], v[52:53] op_sel_hi:[1,0,1]
	v_pk_fma_f32 v[54:55], v[214:215], s[20:21], v[54:55] op_sel_hi:[1,0,1]
	v_lshlrev_b32_e32 v214, 16, v197
	v_and_b32_e32 v215, 0xffff0000, v197
	v_and_b32_e32 v197, 0xffff0000, v196
	v_lshlrev_b32_e32 v196, 16, v196
	v_pk_fma_f32 v[48:49], v[196:197], s[20:21], v[48:49] op_sel_hi:[1,0,1]
	v_pk_fma_f32 v[50:51], v[214:215], s[20:21], v[50:51] op_sel_hi:[1,0,1]
	v_cvt_pk_bf16_f32 v52, v52, v53
	v_cvt_pk_bf16_f32 v53, v54, v55
	v_cvt_pk_bf16_f32 v54, v48, v49
	v_cvt_pk_bf16_f32 v55, v50, v51
	v_add_u32_e32 v48, 0x10000, v140
	global_store_dwordx4 v48, v[52:55], s[8:9] offset:256
	s_waitcnt vmcnt(15)
	v_lshlrev_b32_e32 v214, 16, v199
	v_and_b32_e32 v215, 0xffff0000, v199
	v_and_b32_e32 v199, 0xffff0000, v198
	v_lshlrev_b32_e32 v198, 16, v198
	v_pk_fma_f32 v[44:45], v[198:199], s[20:21], v[44:45] op_sel_hi:[1,0,1]
	v_pk_fma_f32 v[46:47], v[214:215], s[20:21], v[46:47] op_sel_hi:[1,0,1]
	v_lshlrev_b32_e32 v214, 16, v201
	v_and_b32_e32 v215, 0xffff0000, v201
	v_and_b32_e32 v201, 0xffff0000, v200
	v_lshlrev_b32_e32 v200, 16, v200
	v_pk_fma_f32 v[40:41], v[200:201], s[20:21], v[40:41] op_sel_hi:[1,0,1]
	v_pk_fma_f32 v[42:43], v[214:215], s[20:21], v[42:43] op_sel_hi:[1,0,1]
	v_cvt_pk_bf16_f32 v44, v44, v45
	v_cvt_pk_bf16_f32 v45, v46, v47
	v_cvt_pk_bf16_f32 v46, v40, v41
	v_cvt_pk_bf16_f32 v47, v42, v43
	v_add_u32_e32 v40, 0x20000, v140
	global_store_dwordx4 v40, v[44:47], s[8:9] offset:256
	s_waitcnt vmcnt(15)
; __device__ __forceinline__ unsigned cvt_pk_bf16(float lo, float hi) { unsigned r; asm volatile("v_cvt_pk_bf16_f32 %0, %1, %2" : "=v"(r) : "v"(lo), "v"(hi)); return r; }
; __device__ __forceinline__ float bf_lo(unsigned w) { return __uint_as_float(w << 16); }
; __device__ __forceinline__ float bf_hi(unsigned w) { return __uint_as_float(w & 0xffff0000u); }
; #define PG8_GAS __attribute__((address_space(1)))
;     __device__ __forceinline__ void operator()(const f32x4 (&acc)[2][2][4][2], const Unit& u, int wr, int wc, int fr, int fq) const {
;         const int col0 = u.pn * BM + wc * 32 + 8 * fq; const int rowb = u.pm * BM + wr * 64 + fr;
;         const unsigned off0 = (unsigned)(rowb * 2048 + col0);
;     ...
; #pragma unroll
;         for (int bj = 0; bj < 2; ++bj) { const int c = bj * HALF;
;             u32x4 nn = *(const PG8_GAS u32x4*)(res + PG8_ROFF(0) + c);
; #pragma unroll
;             for (int k = 0; k < 8; ++k) { const u32x4 rw = nn;
;                 if (k < 7) nn = *(const PG8_GAS u32x4*)(res + PG8_ROFF(k + 1) + c);
;                 const f32x4 r0 = (f32x4){bf_lo(rw.x), bf_hi(rw.x), bf_lo(rw.y), bf_hi(rw.y)}, r1 = (f32x4){bf_lo(rw.z), bf_hi(rw.z), bf_lo(rw.w), bf_hi(rw.w)};
;                 const unsigned o = PG8_ROFF(k) + c;
;                 const f32x4 y0 = r0 * alpha + acc[k >> 2][bj][k & 3][0], y1 = r1 * alpha + acc[k >> 2][bj][k & 3][1];
;                 u32x4 w; w.x = cvt_pk_bf16(y0[0], y0[1]); w.y = cvt_pk_bf16(y0[2], y0[3]); w.z = cvt_pk_bf16(y1[0], y1[1]); w.w = cvt_pk_bf16(y1[2], y1[3]); *(PG8_GAS u32x4*)(out + o) = w; } }
	v_lshlrev_b32_e32 v214, 16, v203
	v_and_b32_e32 v215, 0xffff0000, v203
	v_and_b32_e32 v203, 0xffff0000, v202
	v_lshlrev_b32_e32 v202, 16, v202
	v_pk_fma_f32 v[36:37], v[202:203], s[20:21], v[36:37] op_sel_hi:[1,0,1]
	v_pk_fma_f32 v[38:39], v[214:215], s[20:21], v[38:39] op_sel_hi:[1,0,1]
	v_lshlrev_b32_e32 v214, 16, v205
	v_and_b32_e32 v215, 0xffff0000, v205
	v_and_b32_e32 v205, 0xffff0000, v204
	v_lshlrev_b32_e32 v204, 16, v204
	v_pk_fma_f32 v[32:33], v[204:205], s[20:21], v[32:33] op_sel_hi:[1,0,1]
	v_pk_fma_f32 v[34:35], v[214:215], s[20:21], v[34:35] op_sel_hi:[1,0,1]
	v_cvt_pk_bf16_f32 v36, v36, v37
	v_cvt_pk_bf16_f32 v37, v38, v39
	v_cvt_pk_bf16_f32 v38, v32, v33
	v_cvt_pk_bf16_f32 v39, v34, v35
	v_add_u32_e32 v32, 0x30000, v140
	global_store_dwordx4 v32, v[36:39], s[8:9] offset:256
	s_waitcnt vmcnt(15)
	v_lshlrev_b32_e32 v214, 16, v207
	v_and_b32_e32 v215, 0xffff0000, v207
	v_and_b32_e32 v207, 0xffff0000, v206
	v_lshlrev_b32_e32 v206, 16, v206
	v_pk_fma_f32 v[28:29], v[206:207], s[20:21], v[28:29] op_sel_hi:[1,0,1]
	v_pk_fma_f32 v[30:31], v[214:215], s[20:21], v[30:31] op_sel_hi:[1,0,1]
	v_lshlrev_b32_e32 v214, 16, v209
	v_and_b32_e32 v215, 0xffff0000, v209
	v_and_b32_e32 v209, 0xffff0000, v208
	v_lshlrev_b32_e32 v208, 16, v208
	v_pk_fma_f32 v[24:25], v[208:209], s[20:21], v[24:25] op_sel_hi:[1,0,1]
	v_pk_fma_f32 v[26:27], v[214:215], s[20:21], v[26:27] op_sel_hi:[1,0,1]
	v_cvt_pk_bf16_f32 v28, v28, v29
	v_cvt_pk_bf16_f32 v29, v30, v31
	v_cvt_pk_bf16_f32 v30, v24, v25
	v_cvt_pk_bf16_f32 v31, v26, v27
	v_add_u32_e32 v24, 0x80000, v140
	global_store_dwordx4 v24, v[28:31], s[8:9] offset:256
	s_waitcnt vmcnt(15)
	v_lshlrev_b32_e32 v214, 16, v211
	v_and_b32_e32 v215, 0xffff0000, v211
	v_and_b32_e32 v211, 0xffff0000, v210
	v_lshlrev_b32_e32 v210, 16, v210
	v_pk_fma_f32 v[20:21], v[210:211], s[20:21], v[20:21] op_sel_hi:[1,0,1]
	v_pk_fma_f32 v[22:23], v[214:215], s[20:21], v[22:23] op_sel_hi:[1,0,1]
	v_lshlrev_b32_e32 v214, 16, v213
	v_and_b32_e32 v215, 0xffff0000, v213
	v_and_b32_e32 v213, 0xffff0000, v212
	v_lshlrev_b32_e32 v212, 16, v212
	v_pk_fma_f32 v[16:17], v[212:213], s[20:21], v[16:17] op_sel_hi:[1,0,1]
	v_pk_fma_f32 v[18:19], v[214:215], s[20:21], v[18:19] op_sel_hi:[1,0,1]
	v_cvt_pk_bf16_f32 v20, v20, v21
	v_cvt_pk_bf16_f32 v21, v22, v23
	v_cvt_pk_bf16_f32 v22, v16, v17
	v_cvt_pk_bf16_f32 v23, v18, v19
	v_add_u32_e32 v16, 0x90000, v140
	global_store_dwordx4 v16, v[20:23], s[8:9] offset:256
	s_waitcnt vmcnt(14)
	v_lshlrev_b32_e32 v214, 16, v151
	v_and_b32_e32 v215, 0xffff0000, v151
	v_and_b32_e32 v151, 0xffff0000, v150
	v_lshlrev_b32_e32 v150, 16, v150
	v_pk_fma_f32 v[12:13], v[150:151], s[20:21], v[12:13] op_sel_hi:[1,0,1]
	v_pk_fma_f32 v[14:15], v[214:215], s[20:21], v[14:15] op_sel_hi:[1,0,1]
	v_lshlrev_b32_e32 v214, 16, v153
	v_and_b32_e32 v215, 0xffff0000, v153
	v_and_b32_e32 v153, 0xffff0000, v152
	v_lshlrev_b32_e32 v152, 16, v152
	v_pk_fma_f32 v[8:9], v[152:153], s[20:21], v[8:9] op_sel_hi:[1,0,1]
	v_pk_fma_f32 v[10:11], v[214:215], s[20:21], v[10:11] op_sel_hi:[1,0,1]
	v_cvt_pk_bf16_f32 v12, v12, v13
	v_cvt_pk_bf16_f32 v13, v14, v15
	v_cvt_pk_bf16_f32 v14, v8, v9
	v_cvt_pk_bf16_f32 v15, v10, v11
	v_add_u32_e32 v8, 0xa0000, v140
	global_store_dwordx4 v8, v[12:15], s[8:9] offset:256
	s_waitcnt vmcnt(13)
	v_lshlrev_b32_e32 v214, 16, v155
	v_and_b32_e32 v215, 0xffff0000, v155
	v_and_b32_e32 v155, 0xffff0000, v154
	v_lshlrev_b32_e32 v154, 16, v154
	v_pk_fma_f32 v[4:5], v[154:155], s[20:21], v[4:5] op_sel_hi:[1,0,1]
	v_pk_fma_f32 v[6:7], v[214:215], s[20:21], v[6:7] op_sel_hi:[1,0,1]
	v_lshlrev_b32_e32 v214, 16, v157
	v_and_b32_e32 v215, 0xffff0000, v157
	v_and_b32_e32 v157, 0xffff0000, v156
	v_lshlrev_b32_e32 v156, 16, v156
	v_pk_fma_f32 v[0:1], v[156:157], s[20:21], v[0:1] op_sel_hi:[1,0,1]
	v_pk_fma_f32 v[2:3], v[214:215], s[20:21], v[2:3] op_sel_hi:[1,0,1]
	v_cvt_pk_bf16_f32 v4, v4, v5
	v_cvt_pk_bf16_f32 v5, v6, v7
	v_cvt_pk_bf16_f32 v6, v0, v1
	v_cvt_pk_bf16_f32 v7, v2, v3
	v_add_u32_e32 v0, 0xb0000, v140
	global_store_dwordx4 v0, v[4:7], s[8:9] offset:256
	s_cbranch_vccnz .LBB0_594
	s_andn2_b64 vcc, exec, s[14:15]
	s_cbranch_vccnz .LBB0_593
	s_barrier
	s_branch .LBB0_593

; __device__ __forceinline__ float fast_sigmoid(float x) { return __builtin_amdgcn_rcpf(1.0f + __builtin_amdgcn_exp2f(-1.4426950408889634f * x)); }
; __device__ __forceinline__ float bf_lo(unsigned w) { return __uint_as_float(w << 16); }
; __device__ __forceinline__ float bf_hi(unsigned w) { return __uint_as_float(w & 0xffff0000u); }
; #define PG8_GAS __attribute__((address_space(1)))
;     __device__ __forceinline__ void operator()(const f32x4 (&acc)[2][2][4][2], const Unit& u, int wr, int wc, int fr, int fq) const {
;         const int col0 = u.pn * BM + wc * 32 + 8 * fq; const int rowb = u.pm * BM + wr * 64 + fr;
;         const unsigned off0 = (unsigned)(rowb * 2048 + col0);
; #pragma unroll
;         for (int bj = 0; bj < 2; ++bj) { const int c = bj * HALF;
;             const f32x4 b0 = *(const PG8_GAS f32x4*)(bias + col0 + c), b1 = *(const PG8_GAS f32x4*)(bias + col0 + c + 4);
;             u32x4 nn = *(const PG8_GAS u32x4*)(res + PG8_ROFF(0) + c), en = *(const PG8_GAS u32x4*)(e + PG8_ROFF(0) + c);
; #pragma unroll
;             for (int k = 0; k < 8; ++k) { const u32x4 rw = nn, ew = en;
;                 if (k < 7) { nn = *(const PG8_GAS u32x4*)(res + PG8_ROFF(k + 1) + c); en = *(const PG8_GAS u32x4*)(e + PG8_ROFF(k + 1) + c); }
;                 const f32x4 r0 = (f32x4){bf_lo(rw.x), bf_hi(rw.x), bf_lo(rw.y), bf_hi(rw.y)}, r1 = (f32x4){bf_lo(rw.z), bf_hi(rw.z), bf_lo(rw.w), bf_hi(rw.w)};
;                 const f32x4 a0 = acc[k >> 2][bj][k & 3][0] + b0, a1 = acc[k >> 2][bj][k & 3][1] + b1;
;                 const f32x4 e0 = (f32x4){bf_lo(ew.x), bf_hi(ew.x), bf_lo(ew.y), bf_hi(ew.y)}, e1 = (f32x4){bf_lo(ew.z), bf_hi(ew.z), bf_lo(ew.w), bf_hi(ew.w)};
;                 f32x4 s0, s1;
; #pragma unroll
;                 for (int i = 0; i < 4; ++i) { s0[i] = fast_sigmoid(a0[i]); s1[i] = fast_sigmoid(a1[i]); }
.LBB0_747:
	v_lshl_or_b32 v160, s70, 8, v173
	s_lshl_b32 s23, s30, 19
	v_add3_u32 v148, s23, v139, v160
	s_andn2_b64 vcc, exec, s[4:5]
	s_mov_b64 s[4:5], -1
	v_lshlrev_b32_e32 v177, 2, v160
	v_lshlrev_b32_e32 v148, 1, v148
	global_load_dwordx4 v[112:115], v177, s[12:13]
	global_load_dwordx4 v[116:119], v177, s[12:13] offset:16
	v_add_u32_e32 v162, 0x0, v148
	global_load_dwordx4 v[166:169], v162, s[62:63]
	global_load_dwordx4 v[162:165], v162, s[68:69]
	v_add_u32_e32 v178, 0x10000, v148
	global_load_dwordx4 v[182:185], v178, s[62:63]
	global_load_dwordx4 v[178:181], v178, s[68:69]
	v_add_u32_e32 v186, 0x20000, v148
	global_load_dwordx4 v[190:193], v186, s[62:63]
	global_load_dwordx4 v[186:189], v186, s[68:69]
	v_add_u32_e32 v194, 0x30000, v148
	global_load_dwordx4 v[198:201], v194, s[62:63]
	global_load_dwordx4 v[194:197], v194, s[68:69]
	v_add_u32_e32 v202, 0x80000, v148
	global_load_dwordx4 v[206:209], v202, s[62:63]
	global_load_dwordx4 v[202:205], v202, s[68:69]
	v_add_u32_e32 v210, 0x90000, v148
	global_load_dwordx4 v[214:217], v210, s[62:63]
	global_load_dwordx4 v[210:213], v210, s[68:69]
	s_waitcnt vmcnt(12)
	v_add_f32_e32 v132, v132, v112
	v_add_f32_e32 v133, v133, v113
	v_add_f32_e32 v134, v134, v114
	v_add_f32_e32 v135, v135, v115
	v_add_f32_e32 v128, v128, v116
	v_add_f32_e32 v129, v129, v117
	v_add_f32_e32 v130, v130, v118
	v_add_f32_e32 v131, v131, v119
	v_mul_f32_e32 v132, 0xbfb8aa3b, v132
	v_mul_f32_e32 v133, 0xbfb8aa3b, v133
	v_mul_f32_e32 v134, 0xbfb8aa3b, v134
	v_mul_f32_e32 v135, 0xbfb8aa3b, v135
	v_mul_f32_e32 v128, 0xbfb8aa3b, v128
	v_mul_f32_e32 v129, 0xbfb8aa3b, v129
	v_mul_f32_e32 v130, 0xbfb8aa3b, v130
	v_mul_f32_e32 v131, 0xbfb8aa3b, v131
	v_exp_f32_e32 v132, v132
	v_exp_f32_e32 v133, v133
	v_exp_f32_e32 v134, v134
	v_exp_f32_e32 v135, v135
	v_exp_f32_e32 v128, v128
	v_exp_f32_e32 v129, v129
	v_exp_f32_e32 v130, v130
	v_exp_f32_e32 v131, v131
	v_add_f32_e32 v132, 1.0, v132
	v_add_f32_e32 v133, 1.0, v133
	v_add_f32_e32 v134, 1.0, v134
	v_add_f32_e32 v135, 1.0, v135
	v_add_f32_e32 v128, 1.0, v128
	v_add_f32_e32 v129, 1.0, v129
	v_add_f32_e32 v130, 1.0, v130
	v_add_f32_e32 v131, 1.0, v131
	v_rcp_f32_e32 v132, v132
	v_rcp_f32_e32 v133, v133
	v_rcp_f32_e32 v134, v134
	v_rcp_f32_e32 v135, v135
	v_rcp_f32_e32 v128, v128
	v_rcp_f32_e32 v129, v129
	v_rcp_f32_e32 v130, v130
	v_rcp_f32_e32 v131, v131
	s_waitcnt vmcnt(10)
	v_lshlrev_b32_e32 v158, 16, v166
	v_and_b32_e32 v159, 0xffff0000, v166
	v_pk_mul_f32 v[132:133], v[132:133], v[158:159]
	v_lshlrev_b32_e32 v158, 16, v162
	v_and_b32_e32 v159, 0xffff0000, v162
	v_pk_fma_f32 v[132:133], v[158:159], s[20:21], v[132:133] op_sel_hi:[1,0,1]
	v_lshlrev_b32_e32 v160, 16, v167
	v_and_b32_e32 v161, 0xffff0000, v167
	v_pk_mul_f32 v[134:135], v[134:135], v[160:161]
	v_lshlrev_b32_e32 v160, 16, v163
	v_and_b32_e32 v161, 0xffff0000, v163
	v_pk_fma_f32 v[134:135], v[160:161], s[20:21], v[134:135] op_sel_hi:[1,0,1]
	v_lshlrev_b32_e32 v158, 16, v168
	v_and_b32_e32 v159, 0xffff0000, v168
	v_pk_mul_f32 v[128:129], v[128:129], v[158:159]
	v_lshlrev_b32_e32 v158, 16, v164
	v_and_b32_e32 v159, 0xffff0000, v164
	v_pk_fma_f32 v[128:129], v[158:159], s[20:21], v[128:129] op_sel_hi:[1,0,1]
	v_lshlrev_b32_e32 v160, 16, v169
	v_and_b32_e32 v161, 0xffff0000, v169
	v_pk_mul_f32 v[130:131], v[130:131], v[160:161]
	v_lshlrev_b32_e32 v160, 16, v165
	v_and_b32_e32 v161, 0xffff0000, v165
	v_pk_fma_f32 v[130:131], v[160:161], s[20:21], v[130:131] op_sel_hi:[1,0,1]
	v_cvt_pk_bf16_f32 v132, v132, v133
	v_cvt_pk_bf16_f32 v133, v134, v135
	v_cvt_pk_bf16_f32 v134, v128, v129
	v_cvt_pk_bf16_f32 v135, v130, v131
	v_add_u32_e32 v128, 0x0, v148
	global_store_dwordx4 v128, v[132:135], s[8:9]
	s_nop 1
	global_load_dwordx4 v[132:135], v177, s[12:13] offset:512
	global_load_dwordx4 v[128:131], v177, s[12:13] offset:528
	v_add_u32_e32 v162, 0xa0000, v148
	global_load_dwordx4 v[166:169], v162, s[62:63]
	global_load_dwordx4 v[162:165], v162, s[68:69]
	v_add_f32_e32 v124, v124, v112
	v_add_f32_e32 v125, v125, v113
	v_add_f32_e32 v126, v126, v114
	v_add_f32_e32 v127, v127, v115
	v_add_f32_e32 v120, v120, v116
	v_add_f32_e32 v121, v121, v117
	v_add_f32_e32 v122, v122, v118
	v_add_f32_e32 v123, v123, v119
	v_mul_f32_e32 v124, 0xbfb8aa3b, v124
	v_mul_f32_e32 v125, 0xbfb8aa3b, v125
	v_mul_f32_e32 v126, 0xbfb8aa3b, v126
	v_mul_f32_e32 v127, 0xbfb8aa3b, v127
	v_mul_f32_e32 v120, 0xbfb8aa3b, v120
	v_mul_f32_e32 v121, 0xbfb8aa3b, v121
	v_mul_f32_e32 v122, 0xbfb8aa3b, v122
	v_mul_f32_e32 v123, 0xbfb8aa3b, v123
	v_exp_f32_e32 v124, v124
	v_exp_f32_e32 v125, v125
	v_exp_f32_e32 v126, v126
	v_exp_f32_e32 v127, v127
	v_exp_f32_e32 v120, v120
	v_exp_f32_e32 v121, v121
	v_exp_f32_e32 v122, v122
	v_exp_f32_e32 v123, v123
	v_add_f32_e32 v124, 1.0, v124
	v_add_f32_e32 v125, 1.0, v125
	v_add_f32_e32 v126, 1.0, v126
	v_add_f32_e32 v127, 1.0, v127
	v_add_f32_e32 v120, 1.0, v120
	v_add_f32_e32 v121, 1.0, v121
	v_add_f32_e32 v122, 1.0, v122
	v_add_f32_e32 v123, 1.0, v123
	v_rcp_f32_e32 v124, v124
	v_rcp_f32_e32 v125, v125
	v_rcp_f32_e32 v126, v126
	v_rcp_f32_e32 v127, v127
	v_rcp_f32_e32 v120, v120
	v_rcp_f32_e32 v121, v121
	v_rcp_f32_e32 v122, v122
	v_rcp_f32_e32 v123, v123
	s_waitcnt vmcnt(13)
; __device__ __forceinline__ unsigned cvt_pk_bf16(float lo, float hi) { unsigned r; asm volatile("v_cvt_pk_bf16_f32 %0, %1, %2" : "=v"(r) : "v"(lo), "v"(hi)); return r; }
; __device__ __forceinline__ float fast_sigmoid(float x) { return __builtin_amdgcn_rcpf(1.0f + __builtin_amdgcn_exp2f(-1.4426950408889634f * x)); }
; __device__ __forceinline__ float bf_lo(unsigned w) { return __uint_as_float(w << 16); }
; __device__ __forceinline__ float bf_hi(unsigned w) { return __uint_as_float(w & 0xffff0000u); }
; #define PG8_GAS __attribute__((address_space(1)))
;     __device__ __forceinline__ void operator()(const f32x4 (&acc)[2][2][4][2], const Unit& u, int wr, int wc, int fr, int fq) const {
;     ...
;         for (int bj = 0; bj < 2; ++bj) { const int c = bj * HALF;
;             const f32x4 b0 = *(const PG8_GAS f32x4*)(bias + col0 + c), b1 = *(const PG8_GAS f32x4*)(bias + col0 + c + 4);
;             u32x4 nn = *(const PG8_GAS u32x4*)(res + PG8_ROFF(0) + c), en = *(const PG8_GAS u32x4*)(e + PG8_ROFF(0) + c);
; #pragma unroll
;             for (int k = 0; k < 8; ++k) { const u32x4 rw = nn, ew = en;
;                 if (k < 7) { nn = *(const PG8_GAS u32x4*)(res + PG8_ROFF(k + 1) + c); en = *(const PG8_GAS u32x4*)(e + PG8_ROFF(k + 1) + c); }
;                 const f32x4 r0 = (f32x4){bf_lo(rw.x), bf_hi(rw.x), bf_lo(rw.y), bf_hi(rw.y)}, r1 = (f32x4){bf_lo(rw.z), bf_hi(rw.z), bf_lo(rw.w), bf_hi(rw.w)};
;                 const f32x4 a0 = acc[k >> 2][bj][k & 3][0] + b0, a1 = acc[k >> 2][bj][k & 3][1] + b1;
;                 const f32x4 e0 = (f32x4){bf_lo(ew.x), bf_hi(ew.x), bf_lo(ew.y), bf_hi(ew.y)}, e1 = (f32x4){bf_lo(ew.z), bf_hi(ew.z), bf_lo(ew.w), bf_hi(ew.w)};
;                 f32x4 s0, s1;
; #pragma unroll
;                 for (int i = 0; i < 4; ++i) { s0[i] = fast_sigmoid(a0[i]); s1[i] = fast_sigmoid(a1[i]); }
;                 const unsigned o = PG8_ROFF(k) + c;
;                 const f32x4 y0 = r0 * alpha + s0 * e0, y1 = r1 * alpha + s1 * e1;
;                 u32x4 w; w.x = cvt_pk_bf16(y0[0], y0[1]); w.y = cvt_pk_bf16(y0[2], y0[3]); w.z = cvt_pk_bf16(y1[0], y1[1]); w.w = cvt_pk_bf16(y1[2], y1[3]); *(PG8_GAS u32x4*)(out + o) = w; } }
	v_lshlrev_b32_e32 v158, 16, v182
	v_and_b32_e32 v159, 0xffff0000, v182
	v_pk_mul_f32 v[124:125], v[124:125], v[158:159]
	v_lshlrev_b32_e32 v158, 16, v178
	v_and_b32_e32 v159, 0xffff0000, v178
	v_pk_fma_f32 v[124:125], v[158:159], s[20:21], v[124:125] op_sel_hi:[1,0,1]
	v_lshlrev_b32_e32 v160, 16, v183
	v_and_b32_e32 v161, 0xffff0000, v183
	v_pk_mul_f32 v[126:127], v[126:127], v[160:161]
	v_lshlrev_b32_e32 v160, 16, v179
	v_and_b32_e32 v161, 0xffff0000, v179
	v_pk_fma_f32 v[126:127], v[160:161], s[20:21], v[126:127] op_sel_hi:[1,0,1]
	v_lshlrev_b32_e32 v158, 16, v184
	v_and_b32_e32 v159, 0xffff0000, v184
	v_pk_mul_f32 v[120:121], v[120:121], v[158:159]
	v_lshlrev_b32_e32 v158, 16, v180
	v_and_b32_e32 v159, 0xffff0000, v180
	v_pk_fma_f32 v[120:121], v[158:159], s[20:21], v[120:121] op_sel_hi:[1,0,1]
	v_lshlrev_b32_e32 v160, 16, v185
	v_and_b32_e32 v161, 0xffff0000, v185
	v_pk_mul_f32 v[122:123], v[122:123], v[160:161]
	v_lshlrev_b32_e32 v160, 16, v181
	v_and_b32_e32 v161, 0xffff0000, v181
	v_pk_fma_f32 v[122:123], v[160:161], s[20:21], v[122:123] op_sel_hi:[1,0,1]
	v_cvt_pk_bf16_f32 v124, v124, v125
	v_cvt_pk_bf16_f32 v125, v126, v127
	v_cvt_pk_bf16_f32 v126, v120, v121
	v_cvt_pk_bf16_f32 v127, v122, v123
	v_add_u32_e32 v120, 0x10000, v148
	global_store_dwordx4 v120, v[124:127], s[8:9]
	v_add_u32_e32 v178, 0xb0000, v148
	global_load_dwordx4 v[182:185], v178, s[62:63]
	global_load_dwordx4 v[178:181], v178, s[68:69]
	v_add_f32_e32 v108, v108, v112
	v_add_f32_e32 v109, v109, v113
	v_add_f32_e32 v110, v110, v114
	v_add_f32_e32 v111, v111, v115
	v_add_f32_e32 v104, v104, v116
	v_add_f32_e32 v105, v105, v117
	v_add_f32_e32 v106, v106, v118
	v_add_f32_e32 v107, v107, v119
	v_mul_f32_e32 v108, 0xbfb8aa3b, v108
	v_mul_f32_e32 v109, 0xbfb8aa3b, v109
	v_mul_f32_e32 v110, 0xbfb8aa3b, v110
	v_mul_f32_e32 v111, 0xbfb8aa3b, v111
	v_mul_f32_e32 v104, 0xbfb8aa3b, v104
	v_mul_f32_e32 v105, 0xbfb8aa3b, v105
	v_mul_f32_e32 v106, 0xbfb8aa3b, v106
	v_mul_f32_e32 v107, 0xbfb8aa3b, v107
	v_exp_f32_e32 v108, v108
	v_exp_f32_e32 v109, v109
	v_exp_f32_e32 v110, v110
	v_exp_f32_e32 v111, v111
	v_exp_f32_e32 v104, v104
	v_exp_f32_e32 v105, v105
	v_exp_f32_e32 v106, v106
	v_exp_f32_e32 v107, v107
	v_add_f32_e32 v108, 1.0, v108
	v_add_f32_e32 v109, 1.0, v109
	v_add_f32_e32 v110, 1.0, v110
	v_add_f32_e32 v111, 1.0, v111
	v_add_f32_e32 v104, 1.0, v104
	v_add_f32_e32 v105, 1.0, v105
	v_add_f32_e32 v106, 1.0, v106
	v_add_f32_e32 v107, 1.0, v107
	v_rcp_f32_e32 v108, v108
	v_rcp_f32_e32 v109, v109
	v_rcp_f32_e32 v110, v110
	v_rcp_f32_e32 v111, v111
	v_rcp_f32_e32 v104, v104
	v_rcp_f32_e32 v105, v105
	v_rcp_f32_e32 v106, v106
	v_rcp_f32_e32 v107, v107
	s_waitcnt vmcnt(14)
	v_lshlrev_b32_e32 v158, 16, v190
	v_and_b32_e32 v159, 0xffff0000, v190
	v_pk_mul_f32 v[108:109], v[108:109], v[158:159]
	v_lshlrev_b32_e32 v158, 16, v186
	v_and_b32_e32 v159, 0xffff0000, v186
	v_pk_fma_f32 v[108:109], v[158:159], s[20:21], v[108:109] op_sel_hi:[1,0,1]
	v_lshlrev_b32_e32 v160, 16, v191
	v_and_b32_e32 v161, 0xffff0000, v191
	v_pk_mul_f32 v[110:111], v[110:111], v[160:161]
	v_lshlrev_b32_e32 v160, 16, v187
	v_and_b32_e32 v161, 0xffff0000, v187
	v_pk_fma_f32 v[110:111], v[160:161], s[20:21], v[110:111] op_sel_hi:[1,0,1]
	v_lshlrev_b32_e32 v158, 16, v192
	v_and_b32_e32 v159, 0xffff0000, v192
	v_pk_mul_f32 v[104:105], v[104:105], v[158:159]
	v_lshlrev_b32_e32 v158, 16, v188
	v_and_b32_e32 v159, 0xffff0000, v188
	v_pk_fma_f32 v[104:105], v[158:159], s[20:21], v[104:105] op_sel_hi:[1,0,1]
	v_lshlrev_b32_e32 v160, 16, v193
	v_and_b32_e32 v161, 0xffff0000, v193
	v_pk_mul_f32 v[106:107], v[106:107], v[160:161]
	v_lshlrev_b32_e32 v160, 16, v189
	v_and_b32_e32 v161, 0xffff0000, v189
	v_pk_fma_f32 v[106:107], v[160:161], s[20:21], v[106:107] op_sel_hi:[1,0,1]
	v_cvt_pk_bf16_f32 v108, v108, v109
	v_cvt_pk_bf16_f32 v109, v110, v111
	v_cvt_pk_bf16_f32 v110, v104, v105
	v_cvt_pk_bf16_f32 v111, v106, v107
	v_add_u32_e32 v104, 0x20000, v148
	global_store_dwordx4 v104, v[108:111], s[8:9]
	v_add_u32_e32 v186, 0x0, v148
	global_load_dwordx4 v[190:193], v186, s[62:63] offset:256
	global_load_dwordx4 v[186:189], v186, s[68:69] offset:256
	v_add_f32_e32 v100, v100, v112
	v_add_f32_e32 v101, v101, v113
	v_add_f32_e32 v102, v102, v114
	v_add_f32_e32 v103, v103, v115
	v_add_f32_e32 v96, v96, v116
	v_add_f32_e32 v97, v97, v117
	v_add_f32_e32 v98, v98, v118
	v_add_f32_e32 v99, v99, v119
	v_mul_f32_e32 v100, 0xbfb8aa3b, v100
	v_mul_f32_e32 v101, 0xbfb8aa3b, v101
	v_mul_f32_e32 v102, 0xbfb8aa3b, v102
	v_mul_f32_e32 v103, 0xbfb8aa3b, v103
	v_mul_f32_e32 v96, 0xbfb8aa3b, v96
	v_mul_f32_e32 v97, 0xbfb8aa3b, v97
	v_mul_f32_e32 v98, 0xbfb8aa3b, v98
	v_mul_f32_e32 v99, 0xbfb8aa3b, v99
	v_exp_f32_e32 v100, v100
	v_exp_f32_e32 v101, v101
	v_exp_f32_e32 v102, v102
	v_exp_f32_e32 v103, v103
	v_exp_f32_e32 v96, v96
	v_exp_f32_e32 v97, v97
	v_exp_f32_e32 v98, v98
	v_exp_f32_e32 v99, v99
	v_add_f32_e32 v100, 1.0, v100
	v_add_f32_e32 v101, 1.0, v101
	v_add_f32_e32 v102, 1.0, v102
	v_add_f32_e32 v103, 1.0, v103
	v_add_f32_e32 v96, 1.0, v96
	v_add_f32_e32 v97, 1.0, v97
	v_add_f32_e32 v98, 1.0, v98
	v_add_f32_e32 v99, 1.0, v99
	v_rcp_f32_e32 v100, v100
	v_rcp_f32_e32 v101, v101
	v_rcp_f32_e32 v102, v102
	v_rcp_f32_e32 v103, v103
	v_rcp_f32_e32 v96, v96
	v_rcp_f32_e32 v97, v97
	v_rcp_f32_e32 v98, v98
	v_rcp_f32_e32 v99, v99
	s_waitcnt vmcnt(15)
; __device__ __forceinline__ unsigned cvt_pk_bf16(float lo, float hi) { unsigned r; asm volatile("v_cvt_pk_bf16_f32 %0, %1, %2" : "=v"(r) : "v"(lo), "v"(hi)); return r; }
; __device__ __forceinline__ float fast_sigmoid(float x) { return __builtin_amdgcn_rcpf(1.0f + __builtin_amdgcn_exp2f(-1.4426950408889634f * x)); }
; __device__ __forceinline__ float bf_lo(unsigned w) { return __uint_as_float(w << 16); }
; __device__ __forceinline__ float bf_hi(unsigned w) { return __uint_as_float(w & 0xffff0000u); }
; #define PG8_GAS __attribute__((address_space(1)))
;     __device__ __forceinline__ void operator()(const f32x4 (&acc)[2][2][4][2], const Unit& u, int wr, int wc, int fr, int fq) const {
;     ...
;         for (int bj = 0; bj < 2; ++bj) { const int c = bj * HALF;
;             const f32x4 b0 = *(const PG8_GAS f32x4*)(bias + col0 + c), b1 = *(const PG8_GAS f32x4*)(bias + col0 + c + 4);
;             u32x4 nn = *(const PG8_GAS u32x4*)(res + PG8_ROFF(0) + c), en = *(const PG8_GAS u32x4*)(e + PG8_ROFF(0) + c);
; #pragma unroll
;             for (int k = 0; k < 8; ++k) { const u32x4 rw = nn, ew = en;
;                 if (k < 7) { nn = *(const PG8_GAS u32x4*)(res + PG8_ROFF(k + 1) + c); en = *(const PG8_GAS u32x4*)(e + PG8_ROFF(k + 1) + c); }
;                 const f32x4 r0 = (f32x4){bf_lo(rw.x), bf_hi(rw.x), bf_lo(rw.y), bf_hi(rw.y)}, r1 = (f32x4){bf_lo(rw.z), bf_hi(rw.z), bf_lo(rw.w), bf_hi(rw.w)};
;                 const f32x4 a0 = acc[k >> 2][bj][k & 3][0] + b0, a1 = acc[k >> 2][bj][k & 3][1] + b1;
;                 const f32x4 e0 = (f32x4){bf_lo(ew.x), bf_hi(ew.x), bf_lo(ew.y), bf_hi(ew.y)}, e1 = (f32x4){bf_lo(ew.z), bf_hi(ew.z), bf_lo(ew.w), bf_hi(ew.w)};
;                 f32x4 s0, s1;
; #pragma unroll
;                 for (int i = 0; i < 4; ++i) { s0[i] = fast_sigmoid(a0[i]); s1[i] = fast_sigmoid(a1[i]); }
;                 const unsigned o = PG8_ROFF(k) + c;
;                 const f32x4 y0 = r0 * alpha + s0 * e0, y1 = r1 * alpha + s1 * e1;
;                 u32x4 w; w.x = cvt_pk_bf16(y0[0], y0[1]); w.y = cvt_pk_bf16(y0[2], y0[3]); w.z = cvt_pk_bf16(y1[0], y1[1]); w.w = cvt_pk_bf16(y1[2], y1[3]); *(PG8_GAS u32x4*)(out + o) = w; } }
	v_lshlrev_b32_e32 v158, 16, v198
	v_and_b32_e32 v159, 0xffff0000, v198
	v_pk_mul_f32 v[100:101], v[100:101], v[158:159]
	v_lshlrev_b32_e32 v158, 16, v194
	v_and_b32_e32 v159, 0xffff0000, v194
	v_pk_fma_f32 v[100:101], v[158:159], s[20:21], v[100:101] op_sel_hi:[1,0,1]
	v_lshlrev_b32_e32 v160, 16, v199
	v_and_b32_e32 v161, 0xffff0000, v199
	v_pk_mul_f32 v[102:103], v[102:103], v[160:161]
	v_lshlrev_b32_e32 v160, 16, v195
	v_and_b32_e32 v161, 0xffff0000, v195
	v_pk_fma_f32 v[102:103], v[160:161], s[20:21], v[102:103] op_sel_hi:[1,0,1]
	v_lshlrev_b32_e32 v158, 16, v200
	v_and_b32_e32 v159, 0xffff0000, v200
	v_pk_mul_f32 v[96:97], v[96:97], v[158:159]
	v_lshlrev_b32_e32 v158, 16, v196
	v_and_b32_e32 v159, 0xffff0000, v196
	v_pk_fma_f32 v[96:97], v[158:159], s[20:21], v[96:97] op_sel_hi:[1,0,1]
	v_lshlrev_b32_e32 v160, 16, v201
	v_and_b32_e32 v161, 0xffff0000, v201
	v_pk_mul_f32 v[98:99], v[98:99], v[160:161]
	v_lshlrev_b32_e32 v160, 16, v197
	v_and_b32_e32 v161, 0xffff0000, v197
	v_pk_fma_f32 v[98:99], v[160:161], s[20:21], v[98:99] op_sel_hi:[1,0,1]
	v_cvt_pk_bf16_f32 v100, v100, v101
	v_cvt_pk_bf16_f32 v101, v102, v103
	v_cvt_pk_bf16_f32 v102, v96, v97
	v_cvt_pk_bf16_f32 v103, v98, v99
	v_add_u32_e32 v96, 0x30000, v148
	global_store_dwordx4 v96, v[100:103], s[8:9]
	v_add_u32_e32 v194, 0x10000, v148
	global_load_dwordx4 v[198:201], v194, s[62:63] offset:256
	global_load_dwordx4 v[194:197], v194, s[68:69] offset:256
	v_add_f32_e32 v92, v92, v112
	v_add_f32_e32 v93, v93, v113
	v_add_f32_e32 v94, v94, v114
	v_add_f32_e32 v95, v95, v115
	v_add_f32_e32 v88, v88, v116
	v_add_f32_e32 v89, v89, v117
	v_add_f32_e32 v90, v90, v118
	v_add_f32_e32 v91, v91, v119
	v_mul_f32_e32 v92, 0xbfb8aa3b, v92
	v_mul_f32_e32 v93, 0xbfb8aa3b, v93
	v_mul_f32_e32 v94, 0xbfb8aa3b, v94
	v_mul_f32_e32 v95, 0xbfb8aa3b, v95
	v_mul_f32_e32 v88, 0xbfb8aa3b, v88
	v_mul_f32_e32 v89, 0xbfb8aa3b, v89
	v_mul_f32_e32 v90, 0xbfb8aa3b, v90
	v_mul_f32_e32 v91, 0xbfb8aa3b, v91
	v_exp_f32_e32 v92, v92
	v_exp_f32_e32 v93, v93
	v_exp_f32_e32 v94, v94
	v_exp_f32_e32 v95, v95
	v_exp_f32_e32 v88, v88
	v_exp_f32_e32 v89, v89
	v_exp_f32_e32 v90, v90
	v_exp_f32_e32 v91, v91
	v_add_f32_e32 v92, 1.0, v92
	v_add_f32_e32 v93, 1.0, v93
	v_add_f32_e32 v94, 1.0, v94
	v_add_f32_e32 v95, 1.0, v95
	v_add_f32_e32 v88, 1.0, v88
	v_add_f32_e32 v89, 1.0, v89
	v_add_f32_e32 v90, 1.0, v90
	v_add_f32_e32 v91, 1.0, v91
	v_rcp_f32_e32 v92, v92
	v_rcp_f32_e32 v93, v93
	v_rcp_f32_e32 v94, v94
	v_rcp_f32_e32 v95, v95
	v_rcp_f32_e32 v88, v88
	v_rcp_f32_e32 v89, v89
	v_rcp_f32_e32 v90, v90
	v_rcp_f32_e32 v91, v91
	s_waitcnt vmcnt(16)
	v_lshlrev_b32_e32 v158, 16, v206
	v_and_b32_e32 v159, 0xffff0000, v206
	v_pk_mul_f32 v[92:93], v[92:93], v[158:159]
	v_lshlrev_b32_e32 v158, 16, v202
	v_and_b32_e32 v159, 0xffff0000, v202
	v_pk_fma_f32 v[92:93], v[158:159], s[20:21], v[92:93] op_sel_hi:[1,0,1]
	v_lshlrev_b32_e32 v160, 16, v207
	v_and_b32_e32 v161, 0xffff0000, v207
	v_pk_mul_f32 v[94:95], v[94:95], v[160:161]
	v_lshlrev_b32_e32 v160, 16, v203
	v_and_b32_e32 v161, 0xffff0000, v203
	v_pk_fma_f32 v[94:95], v[160:161], s[20:21], v[94:95] op_sel_hi:[1,0,1]
	v_lshlrev_b32_e32 v158, 16, v208
	v_and_b32_e32 v159, 0xffff0000, v208
	v_pk_mul_f32 v[88:89], v[88:89], v[158:159]
	v_lshlrev_b32_e32 v158, 16, v204
	v_and_b32_e32 v159, 0xffff0000, v204
	v_pk_fma_f32 v[88:89], v[158:159], s[20:21], v[88:89] op_sel_hi:[1,0,1]
	v_lshlrev_b32_e32 v160, 16, v209
	v_and_b32_e32 v161, 0xffff0000, v209
	v_pk_mul_f32 v[90:91], v[90:91], v[160:161]
	v_lshlrev_b32_e32 v160, 16, v205
	v_and_b32_e32 v161, 0xffff0000, v205
	v_pk_fma_f32 v[90:91], v[160:161], s[20:21], v[90:91] op_sel_hi:[1,0,1]
	v_cvt_pk_bf16_f32 v92, v92, v93
	v_cvt_pk_bf16_f32 v93, v94, v95
	v_cvt_pk_bf16_f32 v94, v88, v89
	v_cvt_pk_bf16_f32 v95, v90, v91
	v_add_u32_e32 v88, 0x80000, v148
	global_store_dwordx4 v88, v[92:95], s[8:9]
	v_add_u32_e32 v202, 0x20000, v148
	global_load_dwordx4 v[206:209], v202, s[62:63] offset:256
	global_load_dwordx4 v[202:205], v202, s[68:69] offset:256
	v_add_f32_e32 v84, v84, v112
	v_add_f32_e32 v85, v85, v113
	v_add_f32_e32 v86, v86, v114
	v_add_f32_e32 v87, v87, v115
	v_add_f32_e32 v80, v80, v116
	v_add_f32_e32 v81, v81, v117
	v_add_f32_e32 v82, v82, v118
	v_add_f32_e32 v83, v83, v119
	v_mul_f32_e32 v84, 0xbfb8aa3b, v84
	v_mul_f32_e32 v85, 0xbfb8aa3b, v85
	v_mul_f32_e32 v86, 0xbfb8aa3b, v86
	v_mul_f32_e32 v87, 0xbfb8aa3b, v87
	v_mul_f32_e32 v80, 0xbfb8aa3b, v80
	v_mul_f32_e32 v81, 0xbfb8aa3b, v81
	v_mul_f32_e32 v82, 0xbfb8aa3b, v82
	v_mul_f32_e32 v83, 0xbfb8aa3b, v83
	v_exp_f32_e32 v84, v84
	v_exp_f32_e32 v85, v85
	v_exp_f32_e32 v86, v86
	v_exp_f32_e32 v87, v87
	v_exp_f32_e32 v80, v80
	v_exp_f32_e32 v81, v81
	v_exp_f32_e32 v82, v82
	v_exp_f32_e32 v83, v83
	v_add_f32_e32 v84, 1.0, v84
	v_add_f32_e32 v85, 1.0, v85
	v_add_f32_e32 v86, 1.0, v86
	v_add_f32_e32 v87, 1.0, v87
	v_add_f32_e32 v80, 1.0, v80
	v_add_f32_e32 v81, 1.0, v81
	v_add_f32_e32 v82, 1.0, v82
	v_add_f32_e32 v83, 1.0, v83
	v_rcp_f32_e32 v84, v84
	v_rcp_f32_e32 v85, v85
	v_rcp_f32_e32 v86, v86
	v_rcp_f32_e32 v87, v87
	v_rcp_f32_e32 v80, v80
	v_rcp_f32_e32 v81, v81
	v_rcp_f32_e32 v82, v82
	v_rcp_f32_e32 v83, v83
	s_waitcnt vmcnt(17)
; __device__ __forceinline__ unsigned cvt_pk_bf16(float lo, float hi) { unsigned r; asm volatile("v_cvt_pk_bf16_f32 %0, %1, %2" : "=v"(r) : "v"(lo), "v"(hi)); return r; }
; __device__ __forceinline__ float fast_sigmoid(float x) { return __builtin_amdgcn_rcpf(1.0f + __builtin_amdgcn_exp2f(-1.4426950408889634f * x)); }
; __device__ __forceinline__ float bf_lo(unsigned w) { return __uint_as_float(w << 16); }
; __device__ __forceinline__ float bf_hi(unsigned w) { return __uint_as_float(w & 0xffff0000u); }
; #define PG8_GAS __attribute__((address_space(1)))
;     __device__ __forceinline__ void operator()(const f32x4 (&acc)[2][2][4][2], const Unit& u, int wr, int wc, int fr, int fq) const {
;     ...
;         for (int bj = 0; bj < 2; ++bj) { const int c = bj * HALF;
;             const f32x4 b0 = *(const PG8_GAS f32x4*)(bias + col0 + c), b1 = *(const PG8_GAS f32x4*)(bias + col0 + c + 4);
;             u32x4 nn = *(const PG8_GAS u32x4*)(res + PG8_ROFF(0) + c), en = *(const PG8_GAS u32x4*)(e + PG8_ROFF(0) + c);
; #pragma unroll
;             for (int k = 0; k < 8; ++k) { const u32x4 rw = nn, ew = en;
;                 if (k < 7) { nn = *(const PG8_GAS u32x4*)(res + PG8_ROFF(k + 1) + c); en = *(const PG8_GAS u32x4*)(e + PG8_ROFF(k + 1) + c); }
;                 const f32x4 r0 = (f32x4){bf_lo(rw.x), bf_hi(rw.x), bf_lo(rw.y), bf_hi(rw.y)}, r1 = (f32x4){bf_lo(rw.z), bf_hi(rw.z), bf_lo(rw.w), bf_hi(rw.w)};
;                 const f32x4 a0 = acc[k >> 2][bj][k & 3][0] + b0, a1 = acc[k >> 2][bj][k & 3][1] + b1;
;                 const f32x4 e0 = (f32x4){bf_lo(ew.x), bf_hi(ew.x), bf_lo(ew.y), bf_hi(ew.y)}, e1 = (f32x4){bf_lo(ew.z), bf_hi(ew.z), bf_lo(ew.w), bf_hi(ew.w)};
;                 f32x4 s0, s1;
; #pragma unroll
;                 for (int i = 0; i < 4; ++i) { s0[i] = fast_sigmoid(a0[i]); s1[i] = fast_sigmoid(a1[i]); }
;                 const unsigned o = PG8_ROFF(k) + c;
;                 const f32x4 y0 = r0 * alpha + s0 * e0, y1 = r1 * alpha + s1 * e1;
;                 u32x4 w; w.x = cvt_pk_bf16(y0[0], y0[1]); w.y = cvt_pk_bf16(y0[2], y0[3]); w.z = cvt_pk_bf16(y1[0], y1[1]); w.w = cvt_pk_bf16(y1[2], y1[3]); *(PG8_GAS u32x4*)(out + o) = w; } }
	v_lshlrev_b32_e32 v158, 16, v214
	v_and_b32_e32 v159, 0xffff0000, v214
	v_pk_mul_f32 v[84:85], v[84:85], v[158:159]
	v_lshlrev_b32_e32 v158, 16, v210
	v_and_b32_e32 v159, 0xffff0000, v210
	v_pk_fma_f32 v[84:85], v[158:159], s[20:21], v[84:85] op_sel_hi:[1,0,1]
	v_lshlrev_b32_e32 v160, 16, v215
	v_and_b32_e32 v161, 0xffff0000, v215
	v_pk_mul_f32 v[86:87], v[86:87], v[160:161]
	v_lshlrev_b32_e32 v160, 16, v211
	v_and_b32_e32 v161, 0xffff0000, v211
	v_pk_fma_f32 v[86:87], v[160:161], s[20:21], v[86:87] op_sel_hi:[1,0,1]
	v_lshlrev_b32_e32 v158, 16, v216
	v_and_b32_e32 v159, 0xffff0000, v216
	v_pk_mul_f32 v[80:81], v[80:81], v[158:159]
	v_lshlrev_b32_e32 v158, 16, v212
	v_and_b32_e32 v159, 0xffff0000, v212
	v_pk_fma_f32 v[80:81], v[158:159], s[20:21], v[80:81] op_sel_hi:[1,0,1]
	v_lshlrev_b32_e32 v160, 16, v217
	v_and_b32_e32 v161, 0xffff0000, v217
	v_pk_mul_f32 v[82:83], v[82:83], v[160:161]
	v_lshlrev_b32_e32 v160, 16, v213
	v_and_b32_e32 v161, 0xffff0000, v213
	v_pk_fma_f32 v[82:83], v[160:161], s[20:21], v[82:83] op_sel_hi:[1,0,1]
	v_cvt_pk_bf16_f32 v84, v84, v85
	v_cvt_pk_bf16_f32 v85, v86, v87
	v_cvt_pk_bf16_f32 v86, v80, v81
	v_cvt_pk_bf16_f32 v87, v82, v83
	v_add_u32_e32 v80, 0x90000, v148
	global_store_dwordx4 v80, v[84:87], s[8:9]
	v_add_u32_e32 v210, 0x30000, v148
	global_load_dwordx4 v[214:217], v210, s[62:63] offset:256
	global_load_dwordx4 v[210:213], v210, s[68:69] offset:256
	v_add_f32_e32 v76, v76, v112
	v_add_f32_e32 v77, v77, v113
	v_add_f32_e32 v78, v78, v114
	v_add_f32_e32 v79, v79, v115
	v_add_f32_e32 v72, v72, v116
	v_add_f32_e32 v73, v73, v117
	v_add_f32_e32 v74, v74, v118
	v_add_f32_e32 v75, v75, v119
	v_mul_f32_e32 v76, 0xbfb8aa3b, v76
	v_mul_f32_e32 v77, 0xbfb8aa3b, v77
	v_mul_f32_e32 v78, 0xbfb8aa3b, v78
	v_mul_f32_e32 v79, 0xbfb8aa3b, v79
	v_mul_f32_e32 v72, 0xbfb8aa3b, v72
	v_mul_f32_e32 v73, 0xbfb8aa3b, v73
	v_mul_f32_e32 v74, 0xbfb8aa3b, v74
	v_mul_f32_e32 v75, 0xbfb8aa3b, v75
	v_exp_f32_e32 v76, v76
	v_exp_f32_e32 v77, v77
	v_exp_f32_e32 v78, v78
	v_exp_f32_e32 v79, v79
	v_exp_f32_e32 v72, v72
	v_exp_f32_e32 v73, v73
	v_exp_f32_e32 v74, v74
	v_exp_f32_e32 v75, v75
	v_add_f32_e32 v76, 1.0, v76
	v_add_f32_e32 v77, 1.0, v77
	v_add_f32_e32 v78, 1.0, v78
	v_add_f32_e32 v79, 1.0, v79
	v_add_f32_e32 v72, 1.0, v72
	v_add_f32_e32 v73, 1.0, v73
	v_add_f32_e32 v74, 1.0, v74
	v_add_f32_e32 v75, 1.0, v75
	v_rcp_f32_e32 v76, v76
	v_rcp_f32_e32 v77, v77
	v_rcp_f32_e32 v78, v78
	v_rcp_f32_e32 v79, v79
	v_rcp_f32_e32 v72, v72
	v_rcp_f32_e32 v73, v73
	v_rcp_f32_e32 v74, v74
	v_rcp_f32_e32 v75, v75
	s_waitcnt vmcnt(15)
	v_lshlrev_b32_e32 v158, 16, v166
	v_and_b32_e32 v159, 0xffff0000, v166
	v_pk_mul_f32 v[76:77], v[76:77], v[158:159]
	v_lshlrev_b32_e32 v158, 16, v162
	v_and_b32_e32 v159, 0xffff0000, v162
	v_pk_fma_f32 v[76:77], v[158:159], s[20:21], v[76:77] op_sel_hi:[1,0,1]
	v_lshlrev_b32_e32 v160, 16, v167
	v_and_b32_e32 v161, 0xffff0000, v167
	v_pk_mul_f32 v[78:79], v[78:79], v[160:161]
	v_lshlrev_b32_e32 v160, 16, v163
	v_and_b32_e32 v161, 0xffff0000, v163
	v_pk_fma_f32 v[78:79], v[160:161], s[20:21], v[78:79] op_sel_hi:[1,0,1]
	v_lshlrev_b32_e32 v158, 16, v168
	v_and_b32_e32 v159, 0xffff0000, v168
	v_pk_mul_f32 v[72:73], v[72:73], v[158:159]
	v_lshlrev_b32_e32 v158, 16, v164
	v_and_b32_e32 v159, 0xffff0000, v164
	v_pk_fma_f32 v[72:73], v[158:159], s[20:21], v[72:73] op_sel_hi:[1,0,1]
	v_lshlrev_b32_e32 v160, 16, v169
	v_and_b32_e32 v161, 0xffff0000, v169
	v_pk_mul_f32 v[74:75], v[74:75], v[160:161]
	v_lshlrev_b32_e32 v160, 16, v165
	v_and_b32_e32 v161, 0xffff0000, v165
	v_pk_fma_f32 v[74:75], v[160:161], s[20:21], v[74:75] op_sel_hi:[1,0,1]
	v_cvt_pk_bf16_f32 v76, v76, v77
	v_cvt_pk_bf16_f32 v77, v78, v79
	v_cvt_pk_bf16_f32 v78, v72, v73
	v_cvt_pk_bf16_f32 v79, v74, v75
	v_add_u32_e32 v72, 0xa0000, v148
	global_store_dwordx4 v72, v[76:79], s[8:9]
	v_add_u32_e32 v162, 0x80000, v148
	global_load_dwordx4 v[166:169], v162, s[62:63] offset:256
	global_load_dwordx4 v[162:165], v162, s[68:69] offset:256
	v_add_f32_e32 v68, v68, v112
	v_add_f32_e32 v69, v69, v113
	v_add_f32_e32 v70, v70, v114
	v_add_f32_e32 v71, v71, v115
	v_add_f32_e32 v64, v64, v116
	v_add_f32_e32 v65, v65, v117
	v_add_f32_e32 v66, v66, v118
	v_add_f32_e32 v67, v67, v119
	v_mul_f32_e32 v68, 0xbfb8aa3b, v68
	v_mul_f32_e32 v69, 0xbfb8aa3b, v69
	v_mul_f32_e32 v70, 0xbfb8aa3b, v70
	v_mul_f32_e32 v71, 0xbfb8aa3b, v71
	v_mul_f32_e32 v64, 0xbfb8aa3b, v64
	v_mul_f32_e32 v65, 0xbfb8aa3b, v65
	v_mul_f32_e32 v66, 0xbfb8aa3b, v66
	v_mul_f32_e32 v67, 0xbfb8aa3b, v67
	v_exp_f32_e32 v68, v68
	v_exp_f32_e32 v69, v69
	v_exp_f32_e32 v70, v70
	v_exp_f32_e32 v71, v71
	v_exp_f32_e32 v64, v64
	v_exp_f32_e32 v65, v65
	v_exp_f32_e32 v66, v66
	v_exp_f32_e32 v67, v67
	v_add_f32_e32 v68, 1.0, v68
	v_add_f32_e32 v69, 1.0, v69
	v_add_f32_e32 v70, 1.0, v70
	v_add_f32_e32 v71, 1.0, v71
	v_add_f32_e32 v64, 1.0, v64
	v_add_f32_e32 v65, 1.0, v65
	v_add_f32_e32 v66, 1.0, v66
	v_add_f32_e32 v67, 1.0, v67
	v_rcp_f32_e32 v68, v68
	v_rcp_f32_e32 v69, v69
	v_rcp_f32_e32 v70, v70
	v_rcp_f32_e32 v71, v71
	v_rcp_f32_e32 v64, v64
	v_rcp_f32_e32 v65, v65
	v_rcp_f32_e32 v66, v66
	v_rcp_f32_e32 v67, v67
	s_waitcnt vmcnt(15)
; __device__ __forceinline__ unsigned cvt_pk_bf16(float lo, float hi) { unsigned r; asm volatile("v_cvt_pk_bf16_f32 %0, %1, %2" : "=v"(r) : "v"(lo), "v"(hi)); return r; }
; __device__ __forceinline__ float fast_sigmoid(float x) { return __builtin_amdgcn_rcpf(1.0f + __builtin_amdgcn_exp2f(-1.4426950408889634f * x)); }
; __device__ __forceinline__ float bf_lo(unsigned w) { return __uint_as_float(w << 16); }
; __device__ __forceinline__ float bf_hi(unsigned w) { return __uint_as_float(w & 0xffff0000u); }
; #define PG8_GAS __attribute__((address_space(1)))
;     __device__ __forceinline__ void operator()(const f32x4 (&acc)[2][2][4][2], const Unit& u, int wr, int wc, int fr, int fq) const {
;     ...
;         for (int bj = 0; bj < 2; ++bj) { const int c = bj * HALF;
;             const f32x4 b0 = *(const PG8_GAS f32x4*)(bias + col0 + c), b1 = *(const PG8_GAS f32x4*)(bias + col0 + c + 4);
;             u32x4 nn = *(const PG8_GAS u32x4*)(res + PG8_ROFF(0) + c), en = *(const PG8_GAS u32x4*)(e + PG8_ROFF(0) + c);
; #pragma unroll
;             for (int k = 0; k < 8; ++k) { const u32x4 rw = nn, ew = en;
;                 if (k < 7) { nn = *(const PG8_GAS u32x4*)(res + PG8_ROFF(k + 1) + c); en = *(const PG8_GAS u32x4*)(e + PG8_ROFF(k + 1) + c); }
;                 const f32x4 r0 = (f32x4){bf_lo(rw.x), bf_hi(rw.x), bf_lo(rw.y), bf_hi(rw.y)}, r1 = (f32x4){bf_lo(rw.z), bf_hi(rw.z), bf_lo(rw.w), bf_hi(rw.w)};
;                 const f32x4 a0 = acc[k >> 2][bj][k & 3][0] + b0, a1 = acc[k >> 2][bj][k & 3][1] + b1;
;                 const f32x4 e0 = (f32x4){bf_lo(ew.x), bf_hi(ew.x), bf_lo(ew.y), bf_hi(ew.y)}, e1 = (f32x4){bf_lo(ew.z), bf_hi(ew.z), bf_lo(ew.w), bf_hi(ew.w)};
;                 f32x4 s0, s1;
; #pragma unroll
;                 for (int i = 0; i < 4; ++i) { s0[i] = fast_sigmoid(a0[i]); s1[i] = fast_sigmoid(a1[i]); }
;                 const unsigned o = PG8_ROFF(k) + c;
;                 const f32x4 y0 = r0 * alpha + s0 * e0, y1 = r1 * alpha + s1 * e1;
;                 u32x4 w; w.x = cvt_pk_bf16(y0[0], y0[1]); w.y = cvt_pk_bf16(y0[2], y0[3]); w.z = cvt_pk_bf16(y1[0], y1[1]); w.w = cvt_pk_bf16(y1[2], y1[3]); *(PG8_GAS u32x4*)(out + o) = w; } }
	v_lshlrev_b32_e32 v158, 16, v182
	v_and_b32_e32 v159, 0xffff0000, v182
	v_pk_mul_f32 v[68:69], v[68:69], v[158:159]
	v_lshlrev_b32_e32 v158, 16, v178
	v_and_b32_e32 v159, 0xffff0000, v178
	v_pk_fma_f32 v[68:69], v[158:159], s[20:21], v[68:69] op_sel_hi:[1,0,1]
	v_lshlrev_b32_e32 v160, 16, v183
	v_and_b32_e32 v161, 0xffff0000, v183
	v_pk_mul_f32 v[70:71], v[70:71], v[160:161]
	v_lshlrev_b32_e32 v160, 16, v179
	v_and_b32_e32 v161, 0xffff0000, v179
	v_pk_fma_f32 v[70:71], v[160:161], s[20:21], v[70:71] op_sel_hi:[1,0,1]
	v_lshlrev_b32_e32 v158, 16, v184
	v_and_b32_e32 v159, 0xffff0000, v184
	v_pk_mul_f32 v[64:65], v[64:65], v[158:159]
	v_lshlrev_b32_e32 v158, 16, v180
	v_and_b32_e32 v159, 0xffff0000, v180
	v_pk_fma_f32 v[64:65], v[158:159], s[20:21], v[64:65] op_sel_hi:[1,0,1]
	v_lshlrev_b32_e32 v160, 16, v185
	v_and_b32_e32 v161, 0xffff0000, v185
	v_pk_mul_f32 v[66:67], v[66:67], v[160:161]
	v_lshlrev_b32_e32 v160, 16, v181
	v_and_b32_e32 v161, 0xffff0000, v181
	v_pk_fma_f32 v[66:67], v[160:161], s[20:21], v[66:67] op_sel_hi:[1,0,1]
	v_cvt_pk_bf16_f32 v68, v68, v69
	v_cvt_pk_bf16_f32 v69, v70, v71
	v_cvt_pk_bf16_f32 v70, v64, v65
	v_cvt_pk_bf16_f32 v71, v66, v67
	v_add_u32_e32 v64, 0xb0000, v148
	global_store_dwordx4 v64, v[68:71], s[8:9]
	v_add_u32_e32 v178, 0x90000, v148
	global_load_dwordx4 v[182:185], v178, s[62:63] offset:256
	global_load_dwordx4 v[178:181], v178, s[68:69] offset:256
	s_waitcnt vmcnt(23)
	v_add_f32_e32 v60, v60, v132
	v_add_f32_e32 v61, v61, v133
	v_add_f32_e32 v62, v62, v134
	v_add_f32_e32 v63, v63, v135
	v_add_f32_e32 v56, v56, v128
	v_add_f32_e32 v57, v57, v129
	v_add_f32_e32 v58, v58, v130
	v_add_f32_e32 v59, v59, v131
	v_mul_f32_e32 v60, 0xbfb8aa3b, v60
	v_mul_f32_e32 v61, 0xbfb8aa3b, v61
	v_mul_f32_e32 v62, 0xbfb8aa3b, v62
	v_mul_f32_e32 v63, 0xbfb8aa3b, v63
	v_mul_f32_e32 v56, 0xbfb8aa3b, v56
	v_mul_f32_e32 v57, 0xbfb8aa3b, v57
	v_mul_f32_e32 v58, 0xbfb8aa3b, v58
	v_mul_f32_e32 v59, 0xbfb8aa3b, v59
	v_exp_f32_e32 v60, v60
	v_exp_f32_e32 v61, v61
	v_exp_f32_e32 v62, v62
	v_exp_f32_e32 v63, v63
	v_exp_f32_e32 v56, v56
	v_exp_f32_e32 v57, v57
	v_exp_f32_e32 v58, v58
	v_exp_f32_e32 v59, v59
	v_add_f32_e32 v60, 1.0, v60
	v_add_f32_e32 v61, 1.0, v61
	v_add_f32_e32 v62, 1.0, v62
	v_add_f32_e32 v63, 1.0, v63
	v_add_f32_e32 v56, 1.0, v56
	v_add_f32_e32 v57, 1.0, v57
	v_add_f32_e32 v58, 1.0, v58
	v_add_f32_e32 v59, 1.0, v59
	v_rcp_f32_e32 v60, v60
	v_rcp_f32_e32 v61, v61
	v_rcp_f32_e32 v62, v62
	v_rcp_f32_e32 v63, v63
	v_rcp_f32_e32 v56, v56
	v_rcp_f32_e32 v57, v57
	v_rcp_f32_e32 v58, v58
	v_rcp_f32_e32 v59, v59
	s_waitcnt vmcnt(15)
	v_lshlrev_b32_e32 v158, 16, v190
	v_and_b32_e32 v159, 0xffff0000, v190
	v_pk_mul_f32 v[60:61], v[60:61], v[158:159]
	v_lshlrev_b32_e32 v158, 16, v186
	v_and_b32_e32 v159, 0xffff0000, v186
	v_pk_fma_f32 v[60:61], v[158:159], s[20:21], v[60:61] op_sel_hi:[1,0,1]
	v_lshlrev_b32_e32 v160, 16, v191
	v_and_b32_e32 v161, 0xffff0000, v191
	v_pk_mul_f32 v[62:63], v[62:63], v[160:161]
	v_lshlrev_b32_e32 v160, 16, v187
	v_and_b32_e32 v161, 0xffff0000, v187
	v_pk_fma_f32 v[62:63], v[160:161], s[20:21], v[62:63] op_sel_hi:[1,0,1]
	v_lshlrev_b32_e32 v158, 16, v192
	v_and_b32_e32 v159, 0xffff0000, v192
	v_pk_mul_f32 v[56:57], v[56:57], v[158:159]
	v_lshlrev_b32_e32 v158, 16, v188
	v_and_b32_e32 v159, 0xffff0000, v188
	v_pk_fma_f32 v[56:57], v[158:159], s[20:21], v[56:57] op_sel_hi:[1,0,1]
	v_lshlrev_b32_e32 v160, 16, v193
	v_and_b32_e32 v161, 0xffff0000, v193
	v_pk_mul_f32 v[58:59], v[58:59], v[160:161]
	v_lshlrev_b32_e32 v160, 16, v189
	v_and_b32_e32 v161, 0xffff0000, v189
	v_pk_fma_f32 v[58:59], v[160:161], s[20:21], v[58:59] op_sel_hi:[1,0,1]
	v_cvt_pk_bf16_f32 v60, v60, v61
	v_cvt_pk_bf16_f32 v61, v62, v63
	v_cvt_pk_bf16_f32 v62, v56, v57
	v_cvt_pk_bf16_f32 v63, v58, v59
	v_add_u32_e32 v56, 0x0, v148
	global_store_dwordx4 v56, v[60:63], s[8:9] offset:256
	v_add_u32_e32 v186, 0xa0000, v148
	global_load_dwordx4 v[190:193], v186, s[62:63] offset:256
	global_load_dwordx4 v[186:189], v186, s[68:69] offset:256
	v_add_f32_e32 v52, v52, v132
	v_add_f32_e32 v53, v53, v133
	v_add_f32_e32 v54, v54, v134
	v_add_f32_e32 v55, v55, v135
	v_add_f32_e32 v48, v48, v128
	v_add_f32_e32 v49, v49, v129
	v_add_f32_e32 v50, v50, v130
	v_add_f32_e32 v51, v51, v131
	v_mul_f32_e32 v52, 0xbfb8aa3b, v52
	v_mul_f32_e32 v53, 0xbfb8aa3b, v53
	v_mul_f32_e32 v54, 0xbfb8aa3b, v54
	v_mul_f32_e32 v55, 0xbfb8aa3b, v55
	v_mul_f32_e32 v48, 0xbfb8aa3b, v48
	v_mul_f32_e32 v49, 0xbfb8aa3b, v49
	v_mul_f32_e32 v50, 0xbfb8aa3b, v50
	v_mul_f32_e32 v51, 0xbfb8aa3b, v51
	v_exp_f32_e32 v52, v52
	v_exp_f32_e32 v53, v53
	v_exp_f32_e32 v54, v54
	v_exp_f32_e32 v55, v55
	v_exp_f32_e32 v48, v48
	v_exp_f32_e32 v49, v49
	v_exp_f32_e32 v50, v50
	v_exp_f32_e32 v51, v51
	v_add_f32_e32 v52, 1.0, v52
	v_add_f32_e32 v53, 1.0, v53
	v_add_f32_e32 v54, 1.0, v54
	v_add_f32_e32 v55, 1.0, v55
	v_add_f32_e32 v48, 1.0, v48
	v_add_f32_e32 v49, 1.0, v49
	v_add_f32_e32 v50, 1.0, v50
	v_add_f32_e32 v51, 1.0, v51
	v_rcp_f32_e32 v52, v52
	v_rcp_f32_e32 v53, v53
	v_rcp_f32_e32 v54, v54
	v_rcp_f32_e32 v55, v55
	v_rcp_f32_e32 v48, v48
	v_rcp_f32_e32 v49, v49
	v_rcp_f32_e32 v50, v50
	v_rcp_f32_e32 v51, v51
	s_waitcnt vmcnt(15)
; __device__ __forceinline__ unsigned cvt_pk_bf16(float lo, float hi) { unsigned r; asm volatile("v_cvt_pk_bf16_f32 %0, %1, %2" : "=v"(r) : "v"(lo), "v"(hi)); return r; }
; __device__ __forceinline__ float fast_sigmoid(float x) { return __builtin_amdgcn_rcpf(1.0f + __builtin_amdgcn_exp2f(-1.4426950408889634f * x)); }
; __device__ __forceinline__ float bf_lo(unsigned w) { return __uint_as_float(w << 16); }
; __device__ __forceinline__ float bf_hi(unsigned w) { return __uint_as_float(w & 0xffff0000u); }
; #define PG8_GAS __attribute__((address_space(1)))
;     __device__ __forceinline__ void operator()(const f32x4 (&acc)[2][2][4][2], const Unit& u, int wr, int wc, int fr, int fq) const {
;     ...
;         for (int bj = 0; bj < 2; ++bj) { const int c = bj * HALF;
;             const f32x4 b0 = *(const PG8_GAS f32x4*)(bias + col0 + c), b1 = *(const PG8_GAS f32x4*)(bias + col0 + c + 4);
;             u32x4 nn = *(const PG8_GAS u32x4*)(res + PG8_ROFF(0) + c), en = *(const PG8_GAS u32x4*)(e + PG8_ROFF(0) + c);
; #pragma unroll
;             for (int k = 0; k < 8; ++k) { const u32x4 rw = nn, ew = en;
;                 if (k < 7) { nn = *(const PG8_GAS u32x4*)(res + PG8_ROFF(k + 1) + c); en = *(const PG8_GAS u32x4*)(e + PG8_ROFF(k + 1) + c); }
;                 const f32x4 r0 = (f32x4){bf_lo(rw.x), bf_hi(rw.x), bf_lo(rw.y), bf_hi(rw.y)}, r1 = (f32x4){bf_lo(rw.z), bf_hi(rw.z), bf_lo(rw.w), bf_hi(rw.w)};
;                 const f32x4 a0 = acc[k >> 2][bj][k & 3][0] + b0, a1 = acc[k >> 2][bj][k & 3][1] + b1;
;                 const f32x4 e0 = (f32x4){bf_lo(ew.x), bf_hi(ew.x), bf_lo(ew.y), bf_hi(ew.y)}, e1 = (f32x4){bf_lo(ew.z), bf_hi(ew.z), bf_lo(ew.w), bf_hi(ew.w)};
;                 f32x4 s0, s1;
; #pragma unroll
;                 for (int i = 0; i < 4; ++i) { s0[i] = fast_sigmoid(a0[i]); s1[i] = fast_sigmoid(a1[i]); }
;                 const unsigned o = PG8_ROFF(k) + c;
;                 const f32x4 y0 = r0 * alpha + s0 * e0, y1 = r1 * alpha + s1 * e1;
;                 u32x4 w; w.x = cvt_pk_bf16(y0[0], y0[1]); w.y = cvt_pk_bf16(y0[2], y0[3]); w.z = cvt_pk_bf16(y1[0], y1[1]); w.w = cvt_pk_bf16(y1[2], y1[3]); *(PG8_GAS u32x4*)(out + o) = w; } }
	v_lshlrev_b32_e32 v158, 16, v198
	v_and_b32_e32 v159, 0xffff0000, v198
	v_pk_mul_f32 v[52:53], v[52:53], v[158:159]
	v_lshlrev_b32_e32 v158, 16, v194
	v_and_b32_e32 v159, 0xffff0000, v194
	v_pk_fma_f32 v[52:53], v[158:159], s[20:21], v[52:53] op_sel_hi:[1,0,1]
	v_lshlrev_b32_e32 v160, 16, v199
	v_and_b32_e32 v161, 0xffff0000, v199
	v_pk_mul_f32 v[54:55], v[54:55], v[160:161]
	v_lshlrev_b32_e32 v160, 16, v195
	v_and_b32_e32 v161, 0xffff0000, v195
	v_pk_fma_f32 v[54:55], v[160:161], s[20:21], v[54:55] op_sel_hi:[1,0,1]
	v_lshlrev_b32_e32 v158, 16, v200
	v_and_b32_e32 v159, 0xffff0000, v200
	v_pk_mul_f32 v[48:49], v[48:49], v[158:159]
	v_lshlrev_b32_e32 v158, 16, v196
	v_and_b32_e32 v159, 0xffff0000, v196
	v_pk_fma_f32 v[48:49], v[158:159], s[20:21], v[48:49] op_sel_hi:[1,0,1]
	v_lshlrev_b32_e32 v160, 16, v201
	v_and_b32_e32 v161, 0xffff0000, v201
	v_pk_mul_f32 v[50:51], v[50:51], v[160:161]
	v_lshlrev_b32_e32 v160, 16, v197
	v_and_b32_e32 v161, 0xffff0000, v197
	v_pk_fma_f32 v[50:51], v[160:161], s[20:21], v[50:51] op_sel_hi:[1,0,1]
	v_cvt_pk_bf16_f32 v52, v52, v53
	v_cvt_pk_bf16_f32 v53, v54, v55
	v_cvt_pk_bf16_f32 v54, v48, v49
	v_cvt_pk_bf16_f32 v55, v50, v51
	v_add_u32_e32 v48, 0x10000, v148
	global_store_dwordx4 v48, v[52:55], s[8:9] offset:256
	v_add_u32_e32 v194, 0xb0000, v148
	global_load_dwordx4 v[198:201], v194, s[62:63] offset:256
	global_load_dwordx4 v[194:197], v194, s[68:69] offset:256
	v_add_f32_e32 v44, v44, v132
	v_add_f32_e32 v45, v45, v133
	v_add_f32_e32 v46, v46, v134
	v_add_f32_e32 v47, v47, v135
	v_add_f32_e32 v40, v40, v128
	v_add_f32_e32 v41, v41, v129
	v_add_f32_e32 v42, v42, v130
	v_add_f32_e32 v43, v43, v131
	v_mul_f32_e32 v44, 0xbfb8aa3b, v44
	v_mul_f32_e32 v45, 0xbfb8aa3b, v45
	v_mul_f32_e32 v46, 0xbfb8aa3b, v46
	v_mul_f32_e32 v47, 0xbfb8aa3b, v47
	v_mul_f32_e32 v40, 0xbfb8aa3b, v40
	v_mul_f32_e32 v41, 0xbfb8aa3b, v41
	v_mul_f32_e32 v42, 0xbfb8aa3b, v42
	v_mul_f32_e32 v43, 0xbfb8aa3b, v43
	v_exp_f32_e32 v44, v44
	v_exp_f32_e32 v45, v45
	v_exp_f32_e32 v46, v46
	v_exp_f32_e32 v47, v47
	v_exp_f32_e32 v40, v40
	v_exp_f32_e32 v41, v41
	v_exp_f32_e32 v42, v42
	v_exp_f32_e32 v43, v43
	v_add_f32_e32 v44, 1.0, v44
	v_add_f32_e32 v45, 1.0, v45
	v_add_f32_e32 v46, 1.0, v46
	v_add_f32_e32 v47, 1.0, v47
	v_add_f32_e32 v40, 1.0, v40
	v_add_f32_e32 v41, 1.0, v41
	v_add_f32_e32 v42, 1.0, v42
	v_add_f32_e32 v43, 1.0, v43
	v_rcp_f32_e32 v44, v44
	v_rcp_f32_e32 v45, v45
	v_rcp_f32_e32 v46, v46
	v_rcp_f32_e32 v47, v47
	v_rcp_f32_e32 v40, v40
	v_rcp_f32_e32 v41, v41
	v_rcp_f32_e32 v42, v42
	v_rcp_f32_e32 v43, v43
	s_waitcnt vmcnt(15)
	v_lshlrev_b32_e32 v158, 16, v206
	v_and_b32_e32 v159, 0xffff0000, v206
	v_pk_mul_f32 v[44:45], v[44:45], v[158:159]
	v_lshlrev_b32_e32 v158, 16, v202
	v_and_b32_e32 v159, 0xffff0000, v202
	v_pk_fma_f32 v[44:45], v[158:159], s[20:21], v[44:45] op_sel_hi:[1,0,1]
	v_lshlrev_b32_e32 v160, 16, v207
	v_and_b32_e32 v161, 0xffff0000, v207
	v_pk_mul_f32 v[46:47], v[46:47], v[160:161]
	v_lshlrev_b32_e32 v160, 16, v203
	v_and_b32_e32 v161, 0xffff0000, v203
	v_pk_fma_f32 v[46:47], v[160:161], s[20:21], v[46:47] op_sel_hi:[1,0,1]
	v_lshlrev_b32_e32 v158, 16, v208
	v_and_b32_e32 v159, 0xffff0000, v208
	v_pk_mul_f32 v[40:41], v[40:41], v[158:159]
	v_lshlrev_b32_e32 v158, 16, v204
	v_and_b32_e32 v159, 0xffff0000, v204
	v_pk_fma_f32 v[40:41], v[158:159], s[20:21], v[40:41] op_sel_hi:[1,0,1]
	v_lshlrev_b32_e32 v160, 16, v209
	v_and_b32_e32 v161, 0xffff0000, v209
	v_pk_mul_f32 v[42:43], v[42:43], v[160:161]
	v_lshlrev_b32_e32 v160, 16, v205
	v_and_b32_e32 v161, 0xffff0000, v205
	v_pk_fma_f32 v[42:43], v[160:161], s[20:21], v[42:43] op_sel_hi:[1,0,1]
	v_cvt_pk_bf16_f32 v44, v44, v45
	v_cvt_pk_bf16_f32 v45, v46, v47
	v_cvt_pk_bf16_f32 v46, v40, v41
	v_cvt_pk_bf16_f32 v47, v42, v43
	v_add_u32_e32 v40, 0x20000, v148
	global_store_dwordx4 v40, v[44:47], s[8:9] offset:256
	v_add_f32_e32 v36, v36, v132
	v_add_f32_e32 v37, v37, v133
	v_add_f32_e32 v38, v38, v134
	v_add_f32_e32 v39, v39, v135
	v_add_f32_e32 v32, v32, v128
	v_add_f32_e32 v33, v33, v129
	v_add_f32_e32 v34, v34, v130
	v_add_f32_e32 v35, v35, v131
	v_mul_f32_e32 v36, 0xbfb8aa3b, v36
	v_mul_f32_e32 v37, 0xbfb8aa3b, v37
	v_mul_f32_e32 v38, 0xbfb8aa3b, v38
	v_mul_f32_e32 v39, 0xbfb8aa3b, v39
	v_mul_f32_e32 v32, 0xbfb8aa3b, v32
	v_mul_f32_e32 v33, 0xbfb8aa3b, v33
	v_mul_f32_e32 v34, 0xbfb8aa3b, v34
	v_mul_f32_e32 v35, 0xbfb8aa3b, v35
	v_exp_f32_e32 v36, v36
	v_exp_f32_e32 v37, v37
	v_exp_f32_e32 v38, v38
	v_exp_f32_e32 v39, v39
	v_exp_f32_e32 v32, v32
	v_exp_f32_e32 v33, v33
	v_exp_f32_e32 v34, v34
	v_exp_f32_e32 v35, v35
	v_add_f32_e32 v36, 1.0, v36
	v_add_f32_e32 v37, 1.0, v37
	v_add_f32_e32 v38, 1.0, v38
	v_add_f32_e32 v39, 1.0, v39
	v_add_f32_e32 v32, 1.0, v32
	v_add_f32_e32 v33, 1.0, v33
	v_add_f32_e32 v34, 1.0, v34
	v_add_f32_e32 v35, 1.0, v35
	v_rcp_f32_e32 v36, v36
	v_rcp_f32_e32 v37, v37
	v_rcp_f32_e32 v38, v38
	v_rcp_f32_e32 v39, v39
	v_rcp_f32_e32 v32, v32
	v_rcp_f32_e32 v33, v33
	v_rcp_f32_e32 v34, v34
	v_rcp_f32_e32 v35, v35
	s_waitcnt vmcnt(13)
; __device__ __forceinline__ unsigned cvt_pk_bf16(float lo, float hi) { unsigned r; asm volatile("v_cvt_pk_bf16_f32 %0, %1, %2" : "=v"(r) : "v"(lo), "v"(hi)); return r; }
; __device__ __forceinline__ float fast_sigmoid(float x) { return __builtin_amdgcn_rcpf(1.0f + __builtin_amdgcn_exp2f(-1.4426950408889634f * x)); }
; __device__ __forceinline__ float bf_lo(unsigned w) { return __uint_as_float(w << 16); }
; __device__ __forceinline__ float bf_hi(unsigned w) { return __uint_as_float(w & 0xffff0000u); }
; #define PG8_GAS __attribute__((address_space(1)))
;     __device__ __forceinline__ void operator()(const f32x4 (&acc)[2][2][4][2], const Unit& u, int wr, int wc, int fr, int fq) const {
;     ...
;         for (int bj = 0; bj < 2; ++bj) { const int c = bj * HALF;
;             const f32x4 b0 = *(const PG8_GAS f32x4*)(bias + col0 + c), b1 = *(const PG8_GAS f32x4*)(bias + col0 + c + 4);
;             u32x4 nn = *(const PG8_GAS u32x4*)(res + PG8_ROFF(0) + c), en = *(const PG8_GAS u32x4*)(e + PG8_ROFF(0) + c);
; #pragma unroll
;             for (int k = 0; k < 8; ++k) { const u32x4 rw = nn, ew = en;
;                 if (k < 7) { nn = *(const PG8_GAS u32x4*)(res + PG8_ROFF(k + 1) + c); en = *(const PG8_GAS u32x4*)(e + PG8_ROFF(k + 1) + c); }
;                 const f32x4 r0 = (f32x4){bf_lo(rw.x), bf_hi(rw.x), bf_lo(rw.y), bf_hi(rw.y)}, r1 = (f32x4){bf_lo(rw.z), bf_hi(rw.z), bf_lo(rw.w), bf_hi(rw.w)};
;                 const f32x4 a0 = acc[k >> 2][bj][k & 3][0] + b0, a1 = acc[k >> 2][bj][k & 3][1] + b1;
;                 const f32x4 e0 = (f32x4){bf_lo(ew.x), bf_hi(ew.x), bf_lo(ew.y), bf_hi(ew.y)}, e1 = (f32x4){bf_lo(ew.z), bf_hi(ew.z), bf_lo(ew.w), bf_hi(ew.w)};
;                 f32x4 s0, s1;
; #pragma unroll
;                 for (int i = 0; i < 4; ++i) { s0[i] = fast_sigmoid(a0[i]); s1[i] = fast_sigmoid(a1[i]); }
;                 const unsigned o = PG8_ROFF(k) + c;
;                 const f32x4 y0 = r0 * alpha + s0 * e0, y1 = r1 * alpha + s1 * e1;
;                 u32x4 w; w.x = cvt_pk_bf16(y0[0], y0[1]); w.y = cvt_pk_bf16(y0[2], y0[3]); w.z = cvt_pk_bf16(y1[0], y1[1]); w.w = cvt_pk_bf16(y1[2], y1[3]); *(PG8_GAS u32x4*)(out + o) = w; } }
	v_lshlrev_b32_e32 v158, 16, v214
	v_and_b32_e32 v159, 0xffff0000, v214
	v_pk_mul_f32 v[36:37], v[36:37], v[158:159]
	v_lshlrev_b32_e32 v158, 16, v210
	v_and_b32_e32 v159, 0xffff0000, v210
	v_pk_fma_f32 v[36:37], v[158:159], s[20:21], v[36:37] op_sel_hi:[1,0,1]
	v_lshlrev_b32_e32 v160, 16, v215
	v_and_b32_e32 v161, 0xffff0000, v215
	v_pk_mul_f32 v[38:39], v[38:39], v[160:161]
	v_lshlrev_b32_e32 v160, 16, v211
	v_and_b32_e32 v161, 0xffff0000, v211
	v_pk_fma_f32 v[38:39], v[160:161], s[20:21], v[38:39] op_sel_hi:[1,0,1]
	v_lshlrev_b32_e32 v158, 16, v216
	v_and_b32_e32 v159, 0xffff0000, v216
	v_pk_mul_f32 v[32:33], v[32:33], v[158:159]
	v_lshlrev_b32_e32 v158, 16, v212
	v_and_b32_e32 v159, 0xffff0000, v212
	v_pk_fma_f32 v[32:33], v[158:159], s[20:21], v[32:33] op_sel_hi:[1,0,1]
	v_lshlrev_b32_e32 v160, 16, v217
	v_and_b32_e32 v161, 0xffff0000, v217
	v_pk_mul_f32 v[34:35], v[34:35], v[160:161]
	v_lshlrev_b32_e32 v160, 16, v213
	v_and_b32_e32 v161, 0xffff0000, v213
	v_pk_fma_f32 v[34:35], v[160:161], s[20:21], v[34:35] op_sel_hi:[1,0,1]
	v_cvt_pk_bf16_f32 v36, v36, v37
	v_cvt_pk_bf16_f32 v37, v38, v39
	v_cvt_pk_bf16_f32 v38, v32, v33
	v_cvt_pk_bf16_f32 v39, v34, v35
	v_add_u32_e32 v32, 0x30000, v148
	global_store_dwordx4 v32, v[36:39], s[8:9] offset:256
	v_add_f32_e32 v28, v28, v132
	v_add_f32_e32 v29, v29, v133
	v_add_f32_e32 v30, v30, v134
	v_add_f32_e32 v31, v31, v135
	v_add_f32_e32 v24, v24, v128
	v_add_f32_e32 v25, v25, v129
	v_add_f32_e32 v26, v26, v130
	v_add_f32_e32 v27, v27, v131
	v_mul_f32_e32 v28, 0xbfb8aa3b, v28
	v_mul_f32_e32 v29, 0xbfb8aa3b, v29
	v_mul_f32_e32 v30, 0xbfb8aa3b, v30
	v_mul_f32_e32 v31, 0xbfb8aa3b, v31
	v_mul_f32_e32 v24, 0xbfb8aa3b, v24
	v_mul_f32_e32 v25, 0xbfb8aa3b, v25
	v_mul_f32_e32 v26, 0xbfb8aa3b, v26
	v_mul_f32_e32 v27, 0xbfb8aa3b, v27
	v_exp_f32_e32 v28, v28
	v_exp_f32_e32 v29, v29
	v_exp_f32_e32 v30, v30
	v_exp_f32_e32 v31, v31
	v_exp_f32_e32 v24, v24
	v_exp_f32_e32 v25, v25
	v_exp_f32_e32 v26, v26
	v_exp_f32_e32 v27, v27
	v_add_f32_e32 v28, 1.0, v28
	v_add_f32_e32 v29, 1.0, v29
	v_add_f32_e32 v30, 1.0, v30
	v_add_f32_e32 v31, 1.0, v31
	v_add_f32_e32 v24, 1.0, v24
	v_add_f32_e32 v25, 1.0, v25
	v_add_f32_e32 v26, 1.0, v26
	v_add_f32_e32 v27, 1.0, v27
	v_rcp_f32_e32 v28, v28
	v_rcp_f32_e32 v29, v29
	v_rcp_f32_e32 v30, v30
	v_rcp_f32_e32 v31, v31
	v_rcp_f32_e32 v24, v24
	v_rcp_f32_e32 v25, v25
	v_rcp_f32_e32 v26, v26
	v_rcp_f32_e32 v27, v27
	s_waitcnt vmcnt(11)
	v_lshlrev_b32_e32 v158, 16, v166
	v_and_b32_e32 v159, 0xffff0000, v166
	v_pk_mul_f32 v[28:29], v[28:29], v[158:159]
	v_lshlrev_b32_e32 v158, 16, v162
	v_and_b32_e32 v159, 0xffff0000, v162
	v_pk_fma_f32 v[28:29], v[158:159], s[20:21], v[28:29] op_sel_hi:[1,0,1]
	v_lshlrev_b32_e32 v160, 16, v167
	v_and_b32_e32 v161, 0xffff0000, v167
	v_pk_mul_f32 v[30:31], v[30:31], v[160:161]
	v_lshlrev_b32_e32 v160, 16, v163
	v_and_b32_e32 v161, 0xffff0000, v163
	v_pk_fma_f32 v[30:31], v[160:161], s[20:21], v[30:31] op_sel_hi:[1,0,1]
	v_lshlrev_b32_e32 v158, 16, v168
	v_and_b32_e32 v159, 0xffff0000, v168
	v_pk_mul_f32 v[24:25], v[24:25], v[158:159]
	v_lshlrev_b32_e32 v158, 16, v164
	v_and_b32_e32 v159, 0xffff0000, v164
	v_pk_fma_f32 v[24:25], v[158:159], s[20:21], v[24:25] op_sel_hi:[1,0,1]
	v_lshlrev_b32_e32 v160, 16, v169
	v_and_b32_e32 v161, 0xffff0000, v169
	v_pk_mul_f32 v[26:27], v[26:27], v[160:161]
	v_lshlrev_b32_e32 v160, 16, v165
	v_and_b32_e32 v161, 0xffff0000, v165
	v_pk_fma_f32 v[26:27], v[160:161], s[20:21], v[26:27] op_sel_hi:[1,0,1]
	v_cvt_pk_bf16_f32 v28, v28, v29
	v_cvt_pk_bf16_f32 v29, v30, v31
	v_cvt_pk_bf16_f32 v30, v24, v25
	v_cvt_pk_bf16_f32 v31, v26, v27
	v_add_u32_e32 v24, 0x80000, v148
	global_store_dwordx4 v24, v[28:31], s[8:9] offset:256
	v_add_f32_e32 v20, v20, v132
	v_add_f32_e32 v21, v21, v133
	v_add_f32_e32 v22, v22, v134
	v_add_f32_e32 v23, v23, v135
	v_add_f32_e32 v16, v16, v128
	v_add_f32_e32 v17, v17, v129
	v_add_f32_e32 v18, v18, v130
	v_add_f32_e32 v19, v19, v131
	v_mul_f32_e32 v20, 0xbfb8aa3b, v20
	v_mul_f32_e32 v21, 0xbfb8aa3b, v21
	v_mul_f32_e32 v22, 0xbfb8aa3b, v22
	v_mul_f32_e32 v23, 0xbfb8aa3b, v23
	v_mul_f32_e32 v16, 0xbfb8aa3b, v16
	v_mul_f32_e32 v17, 0xbfb8aa3b, v17
	v_mul_f32_e32 v18, 0xbfb8aa3b, v18
	v_mul_f32_e32 v19, 0xbfb8aa3b, v19
	v_exp_f32_e32 v20, v20
	v_exp_f32_e32 v21, v21
	v_exp_f32_e32 v22, v22
	v_exp_f32_e32 v23, v23
	v_exp_f32_e32 v16, v16
	v_exp_f32_e32 v17, v17
	v_exp_f32_e32 v18, v18
	v_exp_f32_e32 v19, v19
	v_add_f32_e32 v20, 1.0, v20
	v_add_f32_e32 v21, 1.0, v21
	v_add_f32_e32 v22, 1.0, v22
	v_add_f32_e32 v23, 1.0, v23
	v_add_f32_e32 v16, 1.0, v16
	v_add_f32_e32 v17, 1.0, v17
	v_add_f32_e32 v18, 1.0, v18
	v_add_f32_e32 v19, 1.0, v19
	v_rcp_f32_e32 v20, v20
	v_rcp_f32_e32 v21, v21
	v_rcp_f32_e32 v22, v22
	v_rcp_f32_e32 v23, v23
	v_rcp_f32_e32 v16, v16
	v_rcp_f32_e32 v17, v17
	v_rcp_f32_e32 v18, v18
	v_rcp_f32_e32 v19, v19
	s_waitcnt vmcnt(9)
; __device__ __forceinline__ unsigned cvt_pk_bf16(float lo, float hi) { unsigned r; asm volatile("v_cvt_pk_bf16_f32 %0, %1, %2" : "=v"(r) : "v"(lo), "v"(hi)); return r; }
; __device__ __forceinline__ float fast_sigmoid(float x) { return __builtin_amdgcn_rcpf(1.0f + __builtin_amdgcn_exp2f(-1.4426950408889634f * x)); }
; __device__ __forceinline__ float bf_lo(unsigned w) { return __uint_as_float(w << 16); }
; __device__ __forceinline__ float bf_hi(unsigned w) { return __uint_as_float(w & 0xffff0000u); }
; #define PG8_GAS __attribute__((address_space(1)))
;     __device__ __forceinline__ void operator()(const f32x4 (&acc)[2][2][4][2], const Unit& u, int wr, int wc, int fr, int fq) const {
;     ...
;         for (int bj = 0; bj < 2; ++bj) { const int c = bj * HALF;
;             const f32x4 b0 = *(const PG8_GAS f32x4*)(bias + col0 + c), b1 = *(const PG8_GAS f32x4*)(bias + col0 + c + 4);
;             u32x4 nn = *(const PG8_GAS u32x4*)(res + PG8_ROFF(0) + c), en = *(const PG8_GAS u32x4*)(e + PG8_ROFF(0) + c);
; #pragma unroll
;             for (int k = 0; k < 8; ++k) { const u32x4 rw = nn, ew = en;
;                 if (k < 7) { nn = *(const PG8_GAS u32x4*)(res + PG8_ROFF(k + 1) + c); en = *(const PG8_GAS u32x4*)(e + PG8_ROFF(k + 1) + c); }
;                 const f32x4 r0 = (f32x4){bf_lo(rw.x), bf_hi(rw.x), bf_lo(rw.y), bf_hi(rw.y)}, r1 = (f32x4){bf_lo(rw.z), bf_hi(rw.z), bf_lo(rw.w), bf_hi(rw.w)};
;                 const f32x4 a0 = acc[k >> 2][bj][k & 3][0] + b0, a1 = acc[k >> 2][bj][k & 3][1] + b1;
;                 const f32x4 e0 = (f32x4){bf_lo(ew.x), bf_hi(ew.x), bf_lo(ew.y), bf_hi(ew.y)}, e1 = (f32x4){bf_lo(ew.z), bf_hi(ew.z), bf_lo(ew.w), bf_hi(ew.w)};
;                 f32x4 s0, s1;
; #pragma unroll
;                 for (int i = 0; i < 4; ++i) { s0[i] = fast_sigmoid(a0[i]); s1[i] = fast_sigmoid(a1[i]); }
;                 const unsigned o = PG8_ROFF(k) + c;
;                 const f32x4 y0 = r0 * alpha + s0 * e0, y1 = r1 * alpha + s1 * e1;
;                 u32x4 w; w.x = cvt_pk_bf16(y0[0], y0[1]); w.y = cvt_pk_bf16(y0[2], y0[3]); w.z = cvt_pk_bf16(y1[0], y1[1]); w.w = cvt_pk_bf16(y1[2], y1[3]); *(PG8_GAS u32x4*)(out + o) = w; } }
	v_lshlrev_b32_e32 v158, 16, v182
	v_and_b32_e32 v159, 0xffff0000, v182
	v_pk_mul_f32 v[20:21], v[20:21], v[158:159]
	v_lshlrev_b32_e32 v158, 16, v178
	v_and_b32_e32 v159, 0xffff0000, v178
	v_pk_fma_f32 v[20:21], v[158:159], s[20:21], v[20:21] op_sel_hi:[1,0,1]
	v_lshlrev_b32_e32 v160, 16, v183
	v_and_b32_e32 v161, 0xffff0000, v183
	v_pk_mul_f32 v[22:23], v[22:23], v[160:161]
	v_lshlrev_b32_e32 v160, 16, v179
	v_and_b32_e32 v161, 0xffff0000, v179
	v_pk_fma_f32 v[22:23], v[160:161], s[20:21], v[22:23] op_sel_hi:[1,0,1]
	v_lshlrev_b32_e32 v158, 16, v184
	v_and_b32_e32 v159, 0xffff0000, v184
	v_pk_mul_f32 v[16:17], v[16:17], v[158:159]
	v_lshlrev_b32_e32 v158, 16, v180
	v_and_b32_e32 v159, 0xffff0000, v180
	v_pk_fma_f32 v[16:17], v[158:159], s[20:21], v[16:17] op_sel_hi:[1,0,1]
	v_lshlrev_b32_e32 v160, 16, v185
	v_and_b32_e32 v161, 0xffff0000, v185
	v_pk_mul_f32 v[18:19], v[18:19], v[160:161]
	v_lshlrev_b32_e32 v160, 16, v181
	v_and_b32_e32 v161, 0xffff0000, v181
	v_pk_fma_f32 v[18:19], v[160:161], s[20:21], v[18:19] op_sel_hi:[1,0,1]
	v_cvt_pk_bf16_f32 v20, v20, v21
	v_cvt_pk_bf16_f32 v21, v22, v23
	v_cvt_pk_bf16_f32 v22, v16, v17
	v_cvt_pk_bf16_f32 v23, v18, v19
	v_add_u32_e32 v16, 0x90000, v148
	global_store_dwordx4 v16, v[20:23], s[8:9] offset:256
	v_add_f32_e32 v12, v12, v132
	v_add_f32_e32 v13, v13, v133
	v_add_f32_e32 v14, v14, v134
	v_add_f32_e32 v15, v15, v135
	v_add_f32_e32 v8, v8, v128
	v_add_f32_e32 v9, v9, v129
	v_add_f32_e32 v10, v10, v130
	v_add_f32_e32 v11, v11, v131
	v_mul_f32_e32 v12, 0xbfb8aa3b, v12
	v_mul_f32_e32 v13, 0xbfb8aa3b, v13
	v_mul_f32_e32 v14, 0xbfb8aa3b, v14
	v_mul_f32_e32 v15, 0xbfb8aa3b, v15
	v_mul_f32_e32 v8, 0xbfb8aa3b, v8
	v_mul_f32_e32 v9, 0xbfb8aa3b, v9
	v_mul_f32_e32 v10, 0xbfb8aa3b, v10
	v_mul_f32_e32 v11, 0xbfb8aa3b, v11
	v_exp_f32_e32 v12, v12
	v_exp_f32_e32 v13, v13
	v_exp_f32_e32 v14, v14
	v_exp_f32_e32 v15, v15
	v_exp_f32_e32 v8, v8
	v_exp_f32_e32 v9, v9
	v_exp_f32_e32 v10, v10
	v_exp_f32_e32 v11, v11
	v_add_f32_e32 v12, 1.0, v12
	v_add_f32_e32 v13, 1.0, v13
	v_add_f32_e32 v14, 1.0, v14
	v_add_f32_e32 v15, 1.0, v15
	v_add_f32_e32 v8, 1.0, v8
	v_add_f32_e32 v9, 1.0, v9
	v_add_f32_e32 v10, 1.0, v10
	v_add_f32_e32 v11, 1.0, v11
	v_rcp_f32_e32 v12, v12
	v_rcp_f32_e32 v13, v13
	v_rcp_f32_e32 v14, v14
	v_rcp_f32_e32 v15, v15
	v_rcp_f32_e32 v8, v8
	v_rcp_f32_e32 v9, v9
	v_rcp_f32_e32 v10, v10
	v_rcp_f32_e32 v11, v11
	s_waitcnt vmcnt(7)
	v_lshlrev_b32_e32 v158, 16, v190
	v_and_b32_e32 v159, 0xffff0000, v190
	v_pk_mul_f32 v[12:13], v[12:13], v[158:159]
	v_lshlrev_b32_e32 v158, 16, v186
	v_and_b32_e32 v159, 0xffff0000, v186
	v_pk_fma_f32 v[12:13], v[158:159], s[20:21], v[12:13] op_sel_hi:[1,0,1]
	v_lshlrev_b32_e32 v160, 16, v191
	v_and_b32_e32 v161, 0xffff0000, v191
	v_pk_mul_f32 v[14:15], v[14:15], v[160:161]
	v_lshlrev_b32_e32 v160, 16, v187
	v_and_b32_e32 v161, 0xffff0000, v187
	v_pk_fma_f32 v[14:15], v[160:161], s[20:21], v[14:15] op_sel_hi:[1,0,1]
	v_lshlrev_b32_e32 v158, 16, v192
	v_and_b32_e32 v159, 0xffff0000, v192
	v_pk_mul_f32 v[8:9], v[8:9], v[158:159]
	v_lshlrev_b32_e32 v158, 16, v188
	v_and_b32_e32 v159, 0xffff0000, v188
	v_pk_fma_f32 v[8:9], v[158:159], s[20:21], v[8:9] op_sel_hi:[1,0,1]
	v_lshlrev_b32_e32 v160, 16, v193
	v_and_b32_e32 v161, 0xffff0000, v193
	v_pk_mul_f32 v[10:11], v[10:11], v[160:161]
	v_lshlrev_b32_e32 v160, 16, v189
	v_and_b32_e32 v161, 0xffff0000, v189
	v_pk_fma_f32 v[10:11], v[160:161], s[20:21], v[10:11] op_sel_hi:[1,0,1]
	v_cvt_pk_bf16_f32 v12, v12, v13
	v_cvt_pk_bf16_f32 v13, v14, v15
	v_cvt_pk_bf16_f32 v14, v8, v9
	v_cvt_pk_bf16_f32 v15, v10, v11
	v_add_u32_e32 v8, 0xa0000, v148
	global_store_dwordx4 v8, v[12:15], s[8:9] offset:256
	v_add_f32_e32 v4, v4, v132
	v_add_f32_e32 v5, v5, v133
	v_add_f32_e32 v6, v6, v134
	v_add_f32_e32 v7, v7, v135
	v_add_f32_e32 v0, v0, v128
	v_add_f32_e32 v1, v1, v129
	v_add_f32_e32 v2, v2, v130
	v_add_f32_e32 v3, v3, v131
	v_mul_f32_e32 v4, 0xbfb8aa3b, v4
	v_mul_f32_e32 v5, 0xbfb8aa3b, v5
	v_mul_f32_e32 v6, 0xbfb8aa3b, v6
	v_mul_f32_e32 v7, 0xbfb8aa3b, v7
	v_mul_f32_e32 v0, 0xbfb8aa3b, v0
	v_mul_f32_e32 v1, 0xbfb8aa3b, v1
	v_mul_f32_e32 v2, 0xbfb8aa3b, v2
	v_mul_f32_e32 v3, 0xbfb8aa3b, v3
	v_exp_f32_e32 v4, v4
	v_exp_f32_e32 v5, v5
	v_exp_f32_e32 v6, v6
	v_exp_f32_e32 v7, v7
	v_exp_f32_e32 v0, v0
	v_exp_f32_e32 v1, v1
	v_exp_f32_e32 v2, v2
	v_exp_f32_e32 v3, v3
	v_add_f32_e32 v4, 1.0, v4
	v_add_f32_e32 v5, 1.0, v5
	v_add_f32_e32 v6, 1.0, v6
	v_add_f32_e32 v7, 1.0, v7
	v_add_f32_e32 v0, 1.0, v0
	v_add_f32_e32 v1, 1.0, v1
	v_add_f32_e32 v2, 1.0, v2
	v_add_f32_e32 v3, 1.0, v3
	v_rcp_f32_e32 v4, v4
	v_rcp_f32_e32 v5, v5
	v_rcp_f32_e32 v6, v6
	v_rcp_f32_e32 v7, v7
	v_rcp_f32_e32 v0, v0
	v_rcp_f32_e32 v1, v1
	v_rcp_f32_e32 v2, v2
	v_rcp_f32_e32 v3, v3
	s_waitcnt vmcnt(5)
	v_lshlrev_b32_e32 v158, 16, v198
	v_and_b32_e32 v159, 0xffff0000, v198
	v_pk_mul_f32 v[4:5], v[4:5], v[158:159]
	v_lshlrev_b32_e32 v158, 16, v194
	v_and_b32_e32 v159, 0xffff0000, v194
	v_pk_fma_f32 v[4:5], v[158:159], s[20:21], v[4:5] op_sel_hi:[1,0,1]
	v_lshlrev_b32_e32 v160, 16, v199
	v_and_b32_e32 v161, 0xffff0000, v199
	v_pk_mul_f32 v[6:7], v[6:7], v[160:161]
	v_lshlrev_b32_e32 v160, 16, v195
	v_and_b32_e32 v161, 0xffff0000, v195
	v_pk_fma_f32 v[6:7], v[160:161], s[20:21], v[6:7] op_sel_hi:[1,0,1]
	v_lshlrev_b32_e32 v158, 16, v200
	v_and_b32_e32 v159, 0xffff0000, v200
	v_pk_mul_f32 v[0:1], v[0:1], v[158:159]
	v_lshlrev_b32_e32 v158, 16, v196
	v_and_b32_e32 v159, 0xffff0000, v196
	v_pk_fma_f32 v[0:1], v[158:159], s[20:21], v[0:1] op_sel_hi:[1,0,1]
	v_lshlrev_b32_e32 v160, 16, v201
	v_and_b32_e32 v161, 0xffff0000, v201
	v_pk_mul_f32 v[2:3], v[2:3], v[160:161]
	v_lshlrev_b32_e32 v160, 16, v197
	v_and_b32_e32 v161, 0xffff0000, v197
	v_pk_fma_f32 v[2:3], v[160:161], s[20:21], v[2:3] op_sel_hi:[1,0,1]
	v_cvt_pk_bf16_f32 v4, v4, v5
	v_cvt_pk_bf16_f32 v5, v6, v7
	v_cvt_pk_bf16_f32 v6, v0, v1
	v_cvt_pk_bf16_f32 v7, v2, v3
	v_add_u32_e32 v0, 0xb0000, v148
	global_store_dwordx4 v0, v[4:7], s[8:9] offset:256
	s_cbranch_vccnz .LBB0_736
	s_andn2_b64 vcc, exec, s[14:15]
	s_cbranch_vccnz .LBB0_735
	s_barrier
	s_branch .LBB0_735
